# RWKV scan: next-step kk/kd/v LDS loads issued at step start, w/b/r between DPP levels
# baseline (speedup 1.0000x reference)
.Lrw0_noout:
	ds_read_b64 v[70:71], v1 offset:23936
	ds_read_b64 v[72:73], v1 offset:23552
	ds_read_b64 v[74:75], v1 offset:24320
	ds_read_b64 v[76:77], v1 offset:24064
	ds_read_b64 v[78:79], v1 offset:23680
	ds_read_b64 v[80:81], v1 offset:24448
	ds_read_b64 v[82:83], v1 offset:24192
	ds_read_b64 v[84:85], v1 offset:23808
	ds_read_b64 v[96:97], v1 offset:24576
	ds_read_b64 v[128:129], v2 offset:30464
	ds_read_b64 v[130:131], v2 offset:30592
	v_add_u32_e32 v87, s28, v127
	v_cmp_ne_u32_e32 vcc, 0, v87
	s_nop 1
	v_cndmask_b32_e64 v98, 0, 0.5, vcc
	v_cmp_ne_u32_e32 vcc, s29, v87
	s_nop 1
	v_cndmask_b32_e64 v100, 0, 0.5, vcc
	s_waitcnt lgkmcnt(8)
	v_lshlrev_b32_e32 v132, 16, v70
	v_and_b32_e32 v133, 0xffff0000, v70
	v_lshlrev_b32_e32 v134, 16, v71
	v_and_b32_e32 v135, 0xffff0000, v71
	v_lshlrev_b32_e32 v136, 16, v72
	v_and_b32_e32 v137, 0xffff0000, v72
	v_lshlrev_b32_e32 v138, 16, v73
	v_and_b32_e32 v139, 0xffff0000, v73
	v_lshlrev_b32_e32 v140, 16, v74
	v_and_b32_e32 v141, 0xffff0000, v74
	v_lshlrev_b32_e32 v142, 16, v75
	v_and_b32_e32 v143, 0xffff0000, v75
	v_pk_mul_f32 v[136:137], v[136:137], v[98:99] op_sel_hi:[1,0]
	v_pk_fma_f32 v[136:137], v[140:141], v[100:101], v[136:137] op_sel_hi:[1,0,1]
	v_pk_add_f32 v[136:137], v[136:137], v[132:133] neg_lo:[0,1] neg_hi:[0,1]
	v_pk_fma_f32 v[144:145], v[26:27], v[136:137], v[132:133]
	v_pk_mul_f32 v[138:139], v[138:139], v[98:99] op_sel_hi:[1,0]
	v_pk_fma_f32 v[138:139], v[142:143], v[100:101], v[138:139] op_sel_hi:[1,0,1]
	v_pk_add_f32 v[138:139], v[138:139], v[134:135] neg_lo:[0,1] neg_hi:[0,1]
	v_pk_fma_f32 v[146:147], v[28:29], v[138:139], v[134:135]
	s_waitcnt lgkmcnt(5)
	v_lshlrev_b32_e32 v132, 16, v76
	v_and_b32_e32 v133, 0xffff0000, v76
	v_lshlrev_b32_e32 v134, 16, v77
	v_and_b32_e32 v135, 0xffff0000, v77
	v_lshlrev_b32_e32 v136, 16, v78
	v_and_b32_e32 v137, 0xffff0000, v78
	v_lshlrev_b32_e32 v138, 16, v79
	v_and_b32_e32 v139, 0xffff0000, v79
	v_lshlrev_b32_e32 v140, 16, v80
	v_and_b32_e32 v141, 0xffff0000, v80
	v_lshlrev_b32_e32 v142, 16, v81
	v_and_b32_e32 v143, 0xffff0000, v81
	v_pk_mul_f32 v[136:137], v[136:137], v[98:99] op_sel_hi:[1,0]
	v_pk_fma_f32 v[136:137], v[140:141], v[100:101], v[136:137] op_sel_hi:[1,0,1]
	v_pk_add_f32 v[136:137], v[136:137], v[132:133] neg_lo:[0,1] neg_hi:[0,1]
	v_pk_fma_f32 v[102:103], v[30:31], v[136:137], v[132:133]
	v_pk_mul_f32 v[138:139], v[138:139], v[98:99] op_sel_hi:[1,0]
	v_pk_fma_f32 v[138:139], v[142:143], v[100:101], v[138:139] op_sel_hi:[1,0,1]
	v_pk_add_f32 v[138:139], v[138:139], v[134:135] neg_lo:[0,1] neg_hi:[0,1]
	v_pk_fma_f32 v[104:105], v[32:33], v[138:139], v[134:135]
	s_waitcnt lgkmcnt(2)
	v_lshlrev_b32_e32 v132, 16, v82
	v_and_b32_e32 v133, 0xffff0000, v82
	v_lshlrev_b32_e32 v134, 16, v83
	v_and_b32_e32 v135, 0xffff0000, v83
	v_lshlrev_b32_e32 v136, 16, v84
	v_and_b32_e32 v137, 0xffff0000, v84
	v_lshlrev_b32_e32 v138, 16, v85
	v_and_b32_e32 v139, 0xffff0000, v85
	v_lshlrev_b32_e32 v140, 16, v96
	v_and_b32_e32 v141, 0xffff0000, v96
	v_lshlrev_b32_e32 v142, 16, v97
	v_and_b32_e32 v143, 0xffff0000, v97
	v_pk_mul_f32 v[136:137], v[136:137], v[98:99] op_sel_hi:[1,0]
	v_pk_fma_f32 v[136:137], v[140:141], v[100:101], v[136:137] op_sel_hi:[1,0,1]
	v_pk_add_f32 v[136:137], v[136:137], v[132:133] neg_lo:[0,1] neg_hi:[0,1]
	v_pk_fma_f32 v[148:149], v[34:35], v[136:137], v[132:133]
	v_pk_mul_f32 v[138:139], v[138:139], v[98:99] op_sel_hi:[1,0]
	v_pk_fma_f32 v[138:139], v[142:143], v[100:101], v[138:139] op_sel_hi:[1,0,1]
	v_pk_add_f32 v[138:139], v[138:139], v[134:135] neg_lo:[0,1] neg_hi:[0,1]
	v_pk_fma_f32 v[150:151], v[36:37], v[138:139], v[134:135]
	s_waitcnt lgkmcnt(0)
	v_lshlrev_b32_e32 v132, 16, v128
	v_and_b32_e32 v133, 0xffff0000, v128
	v_lshlrev_b32_e32 v134, 16, v129
	v_and_b32_e32 v135, 0xffff0000, v129
	v_lshlrev_b32_e32 v136, 16, v130
	v_and_b32_e32 v137, 0xffff0000, v130
	v_lshlrev_b32_e32 v138, 16, v131
	v_and_b32_e32 v139, 0xffff0000, v131
	s_mov_b32 s98, 0xbf60028b
	v_mul_f32_e32 v132, s98, v132
	v_mul_f32_e32 v133, s98, v133
	v_mul_f32_e32 v134, s98, v134
	v_mul_f32_e32 v135, s98, v135
	v_exp_f32_e32 v132, v132
	v_exp_f32_e32 v133, v133
	v_exp_f32_e32 v134, v134
	v_exp_f32_e32 v135, v135
	v_pk_mul_f32 v[140:141], v[102:103], v[38:39]
	v_pk_mul_f32 v[142:143], v[104:105], v[40:41]
	v_pk_mul_f32 v[106:107], v[140:141], v[140:141]
	v_pk_fma_f32 v[106:107], v[142:143], v[142:143], v[106:107]
	v_add_f32_e32 v106, v106, v107
	s_nop 1
	v_add_f32_dpp v106, v106, v106 row_ror:8 row_mask:0xf bank_mask:0xf bound_ctrl:1
	s_nop 1
	v_add_f32_dpp v106, v106, v106 row_ror:4 row_mask:0xf bank_mask:0xf bound_ctrl:1
	s_nop 1
	v_add_f32_dpp v106, v106, v106 row_ror:2 row_mask:0xf bank_mask:0xf bound_ctrl:1
	s_nop 1
	v_add_f32_dpp v106, v106, v106 row_ror:1 row_mask:0xf bank_mask:0xf bound_ctrl:1
	v_add_f32_e32 v106, 0x2b8cbccc, v106
	v_rsq_f32_e32 v106, v106
	v_pk_mul_f32 v[148:149], v[148:149], s[40:41] op_sel_hi:[1,0]
	v_pk_mul_f32 v[150:151], v[150:151], s[40:41] op_sel_hi:[1,0]
	v_pk_mul_f32 v[140:141], v[140:141], v[106:107] op_sel_hi:[1,0]
	v_pk_mul_f32 v[142:143], v[142:143], v[106:107] op_sel_hi:[1,0]
	v_pk_add_f32 v[70:71], v[136:137], -1.0 op_sel_hi:[1,0]
	v_pk_add_f32 v[72:73], v[138:139], -1.0 op_sel_hi:[1,0]
	v_pk_fma_f32 v[70:71], v[42:43], v[70:71], 1.0 op_sel_hi:[1,1,0]
	v_pk_fma_f32 v[72:73], v[44:45], v[72:73], 1.0 op_sel_hi:[1,1,0]
	v_pk_mul_f32 v[70:71], v[102:103], v[70:71]
	v_pk_mul_f32 v[72:73], v[104:105], v[72:73]
	v_pk_mul_f32 v[74:75], v[140:141], v[136:137]
	v_pk_mul_f32 v[76:77], v[142:143], v[138:139]
	ds_write_b128 v3, v[140:143] offset:0
	ds_write_b128 v3, v[132:135] offset:4096
	ds_write_b128 v3, v[74:77] offset:8192
	ds_write_b128 v3, v[70:73] offset:12288
	ds_write_b128 v3, v[144:147] offset:16384
	ds_write_b128 v4, v[148:151]
	s_waitcnt lgkmcnt(0)
	s_barrier
	ds_read_b128 v[70:73], v95 offset:0
	ds_read_b128 v[82:85], v95 offset:12288
	ds_read_b32 v100, v108 offset:20480
	ds_read_b128 v[74:77], v95 offset:4096
	ds_read_b128 v[78:81], v95 offset:8192
	ds_read_b128 v[96:99], v95 offset:16384
	ds_read_b128 v[128:131], v95 offset:256
	ds_read_b128 v[140:143], v95 offset:12544
	ds_read_b32 v148, v108 offset:20544
	s_waitcnt lgkmcnt(8)
	v_pk_mul_f32 v[102:103], v[22:23], v[70:71]
	s_waitcnt lgkmcnt(6)
	v_pk_mul_f32 v[104:105], v[82:83], v[100:101] op_sel_hi:[1,0]
	v_pk_fma_f32 v[102:103], v[24:25], v[72:73], v[102:103]
	v_pk_mul_f32 v[106:107], v[84:85], v[100:101] op_sel_hi:[1,0]
	v_add_f32_e32 v112, v102, v103
	s_waitcnt lgkmcnt(5)
	v_pk_fma_f32 v[104:105], v[22:23], v[74:75], v[104:105]
	v_pk_fma_f32 v[106:107], v[24:25], v[76:77], v[106:107]
	v_add_f32_dpp v112, v112, v112 row_ror:8 row_mask:0xf bank_mask:0xf bound_ctrl:1
	ds_read_b128 v[132:135], v95 offset:4352
	s_nop 0
	v_add_f32_dpp v112, v112, v112 row_ror:4 row_mask:0xf bank_mask:0xf bound_ctrl:1
	ds_read_b128 v[136:139], v95 offset:8448
	s_nop 0
	v_add_f32_dpp v112, v112, v112 row_ror:2 row_mask:0xf bank_mask:0xf bound_ctrl:1
	ds_read_b128 v[144:147], v95 offset:16640
	s_nop 0
	v_add_f32_dpp v112, v112, v112 row_ror:1 row_mask:0xf bank_mask:0xf bound_ctrl:1
	s_waitcnt lgkmcnt(7)
	v_pk_fma_f32 v[22:23], v[112:113], v[78:79], v[104:105] op_sel_hi:[0,1,1] neg_lo:[1,0,0] neg_hi:[1,0,0]
	v_pk_fma_f32 v[24:25], v[112:113], v[80:81], v[106:107] op_sel_hi:[0,1,1] neg_lo:[1,0,0] neg_hi:[1,0,0]
	ds_read_b128 v[70:73], v95 offset:512
	ds_read_b128 v[82:85], v95 offset:12800
	ds_read_b32 v100, v108 offset:20608
	s_waitcnt lgkmcnt(8)
	v_pk_mul_f32 v[102:103], v[22:23], v[128:129]
	s_waitcnt lgkmcnt(6)
	v_pk_mul_f32 v[104:105], v[140:141], v[148:149] op_sel_hi:[1,0]
	v_pk_fma_f32 v[102:103], v[24:25], v[130:131], v[102:103]
	v_pk_mul_f32 v[106:107], v[142:143], v[148:149] op_sel_hi:[1,0]
	v_pk_mul_f32 v[150:151], v[96:97], v[22:23]
	v_add_f32_e32 v112, v102, v103
	v_pk_fma_f32 v[150:151], v[98:99], v[24:25], v[150:151]
	s_waitcnt lgkmcnt(5)
	v_pk_fma_f32 v[104:105], v[22:23], v[132:133], v[104:105]
	v_add_f32_e32 v114, v150, v151
	v_pk_fma_f32 v[106:107], v[24:25], v[134:135], v[106:107]
	v_add_f32_dpp v112, v112, v112 row_ror:8 row_mask:0xf bank_mask:0xf bound_ctrl:1
	v_add_f32_dpp v114, v114, v114 row_ror:8 row_mask:0xf bank_mask:0xf bound_ctrl:1
	ds_read_b128 v[74:77], v95 offset:4608
	v_add_f32_dpp v112, v112, v112 row_ror:4 row_mask:0xf bank_mask:0xf bound_ctrl:1
	v_add_f32_dpp v114, v114, v114 row_ror:4 row_mask:0xf bank_mask:0xf bound_ctrl:1
	ds_read_b128 v[78:81], v95 offset:8704
	v_add_f32_dpp v112, v112, v112 row_ror:2 row_mask:0xf bank_mask:0xf bound_ctrl:1
	v_add_f32_dpp v114, v114, v114 row_ror:2 row_mask:0xf bank_mask:0xf bound_ctrl:1
	ds_read_b128 v[96:99], v95 offset:16896
	v_add_f32_dpp v112, v112, v112 row_ror:1 row_mask:0xf bank_mask:0xf bound_ctrl:1
	v_add_f32_dpp v114, v114, v114 row_ror:1 row_mask:0xf bank_mask:0xf bound_ctrl:1
	s_waitcnt lgkmcnt(7)
	v_pk_fma_f32 v[22:23], v[112:113], v[136:137], v[104:105] op_sel_hi:[0,1,1] neg_lo:[1,0,0] neg_hi:[1,0,0]
	v_pk_fma_f32 v[24:25], v[112:113], v[138:139], v[106:107] op_sel_hi:[0,1,1] neg_lo:[1,0,0] neg_hi:[1,0,0]
	ds_write_b32 v108, v114 offset:21504
	ds_read_b128 v[128:131], v95 offset:768
	ds_read_b128 v[140:143], v95 offset:13056
	ds_read_b32 v148, v108 offset:20672
	s_waitcnt lgkmcnt(9)
	v_pk_mul_f32 v[102:103], v[22:23], v[70:71]
	s_waitcnt lgkmcnt(7)
	v_pk_mul_f32 v[104:105], v[82:83], v[100:101] op_sel_hi:[1,0]
	v_pk_fma_f32 v[102:103], v[24:25], v[72:73], v[102:103]
	v_pk_mul_f32 v[106:107], v[84:85], v[100:101] op_sel_hi:[1,0]
	v_pk_mul_f32 v[150:151], v[144:145], v[22:23]
	v_add_f32_e32 v112, v102, v103
	v_pk_fma_f32 v[150:151], v[146:147], v[24:25], v[150:151]
	s_waitcnt lgkmcnt(6)
	v_pk_fma_f32 v[104:105], v[22:23], v[74:75], v[104:105]
	v_add_f32_e32 v114, v150, v151
	v_pk_fma_f32 v[106:107], v[24:25], v[76:77], v[106:107]
	v_add_f32_dpp v112, v112, v112 row_ror:8 row_mask:0xf bank_mask:0xf bound_ctrl:1
	v_add_f32_dpp v114, v114, v114 row_ror:8 row_mask:0xf bank_mask:0xf bound_ctrl:1
	ds_read_b128 v[132:135], v95 offset:4864
	v_add_f32_dpp v112, v112, v112 row_ror:4 row_mask:0xf bank_mask:0xf bound_ctrl:1
	v_add_f32_dpp v114, v114, v114 row_ror:4 row_mask:0xf bank_mask:0xf bound_ctrl:1
	ds_read_b128 v[136:139], v95 offset:8960
	v_add_f32_dpp v112, v112, v112 row_ror:2 row_mask:0xf bank_mask:0xf bound_ctrl:1
	v_add_f32_dpp v114, v114, v114 row_ror:2 row_mask:0xf bank_mask:0xf bound_ctrl:1
	ds_read_b128 v[144:147], v95 offset:17152
	v_add_f32_dpp v112, v112, v112 row_ror:1 row_mask:0xf bank_mask:0xf bound_ctrl:1
	v_add_f32_dpp v114, v114, v114 row_ror:1 row_mask:0xf bank_mask:0xf bound_ctrl:1
	s_waitcnt lgkmcnt(8)
	v_pk_fma_f32 v[22:23], v[112:113], v[78:79], v[104:105] op_sel_hi:[0,1,1] neg_lo:[1,0,0] neg_hi:[1,0,0]
	v_pk_fma_f32 v[24:25], v[112:113], v[80:81], v[106:107] op_sel_hi:[0,1,1] neg_lo:[1,0,0] neg_hi:[1,0,0]
	ds_write_b32 v108, v114 offset:21568
	ds_read_b128 v[70:73], v95 offset:1024
	ds_read_b128 v[82:85], v95 offset:13312
	ds_read_b32 v100, v108 offset:20736
	s_waitcnt lgkmcnt(9)
	v_pk_mul_f32 v[102:103], v[22:23], v[128:129]
	s_waitcnt lgkmcnt(7)
	v_pk_mul_f32 v[104:105], v[140:141], v[148:149] op_sel_hi:[1,0]
	v_pk_fma_f32 v[102:103], v[24:25], v[130:131], v[102:103]
	v_pk_mul_f32 v[106:107], v[142:143], v[148:149] op_sel_hi:[1,0]
	v_pk_mul_f32 v[150:151], v[96:97], v[22:23]
	v_add_f32_e32 v112, v102, v103
	v_pk_fma_f32 v[150:151], v[98:99], v[24:25], v[150:151]
	s_waitcnt lgkmcnt(6)
	v_pk_fma_f32 v[104:105], v[22:23], v[132:133], v[104:105]
	v_add_f32_e32 v114, v150, v151
	v_pk_fma_f32 v[106:107], v[24:25], v[134:135], v[106:107]
	v_add_f32_dpp v112, v112, v112 row_ror:8 row_mask:0xf bank_mask:0xf bound_ctrl:1
	v_add_f32_dpp v114, v114, v114 row_ror:8 row_mask:0xf bank_mask:0xf bound_ctrl:1
	ds_read_b128 v[74:77], v95 offset:5120
	v_add_f32_dpp v112, v112, v112 row_ror:4 row_mask:0xf bank_mask:0xf bound_ctrl:1
	v_add_f32_dpp v114, v114, v114 row_ror:4 row_mask:0xf bank_mask:0xf bound_ctrl:1
	ds_read_b128 v[78:81], v95 offset:9216
	v_add_f32_dpp v112, v112, v112 row_ror:2 row_mask:0xf bank_mask:0xf bound_ctrl:1
	v_add_f32_dpp v114, v114, v114 row_ror:2 row_mask:0xf bank_mask:0xf bound_ctrl:1
	ds_read_b128 v[96:99], v95 offset:17408
	v_add_f32_dpp v112, v112, v112 row_ror:1 row_mask:0xf bank_mask:0xf bound_ctrl:1
	v_add_f32_dpp v114, v114, v114 row_ror:1 row_mask:0xf bank_mask:0xf bound_ctrl:1
	s_waitcnt lgkmcnt(8)
	v_pk_fma_f32 v[22:23], v[112:113], v[136:137], v[104:105] op_sel_hi:[0,1,1] neg_lo:[1,0,0] neg_hi:[1,0,0]
	v_pk_fma_f32 v[24:25], v[112:113], v[138:139], v[106:107] op_sel_hi:[0,1,1] neg_lo:[1,0,0] neg_hi:[1,0,0]
	ds_write_b32 v108, v114 offset:21632
	ds_read_b128 v[128:131], v95 offset:1280
	ds_read_b128 v[140:143], v95 offset:13568
	ds_read_b32 v148, v108 offset:20800
	s_waitcnt lgkmcnt(9)
	v_pk_mul_f32 v[102:103], v[22:23], v[70:71]
	s_waitcnt lgkmcnt(7)
	v_pk_mul_f32 v[104:105], v[82:83], v[100:101] op_sel_hi:[1,0]
	v_pk_fma_f32 v[102:103], v[24:25], v[72:73], v[102:103]
	v_pk_mul_f32 v[106:107], v[84:85], v[100:101] op_sel_hi:[1,0]
	v_pk_mul_f32 v[150:151], v[144:145], v[22:23]
	v_add_f32_e32 v112, v102, v103
	v_pk_fma_f32 v[150:151], v[146:147], v[24:25], v[150:151]
	s_waitcnt lgkmcnt(6)
	v_pk_fma_f32 v[104:105], v[22:23], v[74:75], v[104:105]
	v_add_f32_e32 v114, v150, v151
	v_pk_fma_f32 v[106:107], v[24:25], v[76:77], v[106:107]
	v_add_f32_dpp v112, v112, v112 row_ror:8 row_mask:0xf bank_mask:0xf bound_ctrl:1
	v_add_f32_dpp v114, v114, v114 row_ror:8 row_mask:0xf bank_mask:0xf bound_ctrl:1
	ds_read_b128 v[132:135], v95 offset:5376
	v_add_f32_dpp v112, v112, v112 row_ror:4 row_mask:0xf bank_mask:0xf bound_ctrl:1
	v_add_f32_dpp v114, v114, v114 row_ror:4 row_mask:0xf bank_mask:0xf bound_ctrl:1
	ds_read_b128 v[136:139], v95 offset:9472
	v_add_f32_dpp v112, v112, v112 row_ror:2 row_mask:0xf bank_mask:0xf bound_ctrl:1
	v_add_f32_dpp v114, v114, v114 row_ror:2 row_mask:0xf bank_mask:0xf bound_ctrl:1
	ds_read_b128 v[144:147], v95 offset:17664
	v_add_f32_dpp v112, v112, v112 row_ror:1 row_mask:0xf bank_mask:0xf bound_ctrl:1
	v_add_f32_dpp v114, v114, v114 row_ror:1 row_mask:0xf bank_mask:0xf bound_ctrl:1
	s_waitcnt lgkmcnt(8)
	v_pk_fma_f32 v[22:23], v[112:113], v[78:79], v[104:105] op_sel_hi:[0,1,1] neg_lo:[1,0,0] neg_hi:[1,0,0]
	v_pk_fma_f32 v[24:25], v[112:113], v[80:81], v[106:107] op_sel_hi:[0,1,1] neg_lo:[1,0,0] neg_hi:[1,0,0]
	ds_write_b32 v108, v114 offset:21696
	ds_read_b128 v[70:73], v95 offset:1536
	ds_read_b128 v[82:85], v95 offset:13824
	ds_read_b32 v100, v108 offset:20864
	s_waitcnt lgkmcnt(9)
	v_pk_mul_f32 v[102:103], v[22:23], v[128:129]
	s_waitcnt lgkmcnt(7)
	v_pk_mul_f32 v[104:105], v[140:141], v[148:149] op_sel_hi:[1,0]
	v_pk_fma_f32 v[102:103], v[24:25], v[130:131], v[102:103]
	v_pk_mul_f32 v[106:107], v[142:143], v[148:149] op_sel_hi:[1,0]
	v_pk_mul_f32 v[150:151], v[96:97], v[22:23]
	v_add_f32_e32 v112, v102, v103
	v_pk_fma_f32 v[150:151], v[98:99], v[24:25], v[150:151]
	s_waitcnt lgkmcnt(6)
	v_pk_fma_f32 v[104:105], v[22:23], v[132:133], v[104:105]
	v_add_f32_e32 v114, v150, v151
	v_pk_fma_f32 v[106:107], v[24:25], v[134:135], v[106:107]
	v_add_f32_dpp v112, v112, v112 row_ror:8 row_mask:0xf bank_mask:0xf bound_ctrl:1
	v_add_f32_dpp v114, v114, v114 row_ror:8 row_mask:0xf bank_mask:0xf bound_ctrl:1
	ds_read_b128 v[74:77], v95 offset:5632
	v_add_f32_dpp v112, v112, v112 row_ror:4 row_mask:0xf bank_mask:0xf bound_ctrl:1
	v_add_f32_dpp v114, v114, v114 row_ror:4 row_mask:0xf bank_mask:0xf bound_ctrl:1
	ds_read_b128 v[78:81], v95 offset:9728
	v_add_f32_dpp v112, v112, v112 row_ror:2 row_mask:0xf bank_mask:0xf bound_ctrl:1
	v_add_f32_dpp v114, v114, v114 row_ror:2 row_mask:0xf bank_mask:0xf bound_ctrl:1
	ds_read_b128 v[96:99], v95 offset:17920
	v_add_f32_dpp v112, v112, v112 row_ror:1 row_mask:0xf bank_mask:0xf bound_ctrl:1
	v_add_f32_dpp v114, v114, v114 row_ror:1 row_mask:0xf bank_mask:0xf bound_ctrl:1
	s_waitcnt lgkmcnt(8)
	v_pk_fma_f32 v[22:23], v[112:113], v[136:137], v[104:105] op_sel_hi:[0,1,1] neg_lo:[1,0,0] neg_hi:[1,0,0]
	v_pk_fma_f32 v[24:25], v[112:113], v[138:139], v[106:107] op_sel_hi:[0,1,1] neg_lo:[1,0,0] neg_hi:[1,0,0]
	ds_write_b32 v108, v114 offset:21760
	ds_read_b128 v[128:131], v95 offset:1792
	ds_read_b128 v[140:143], v95 offset:14080
	ds_read_b32 v148, v108 offset:20928
	s_waitcnt lgkmcnt(9)
	v_pk_mul_f32 v[102:103], v[22:23], v[70:71]
	s_waitcnt lgkmcnt(7)
	v_pk_mul_f32 v[104:105], v[82:83], v[100:101] op_sel_hi:[1,0]
	v_pk_fma_f32 v[102:103], v[24:25], v[72:73], v[102:103]
	v_pk_mul_f32 v[106:107], v[84:85], v[100:101] op_sel_hi:[1,0]
	v_pk_mul_f32 v[150:151], v[144:145], v[22:23]
	v_add_f32_e32 v112, v102, v103
	v_pk_fma_f32 v[150:151], v[146:147], v[24:25], v[150:151]
	s_waitcnt lgkmcnt(6)
	v_pk_fma_f32 v[104:105], v[22:23], v[74:75], v[104:105]
	v_add_f32_e32 v114, v150, v151
	v_pk_fma_f32 v[106:107], v[24:25], v[76:77], v[106:107]
	v_add_f32_dpp v112, v112, v112 row_ror:8 row_mask:0xf bank_mask:0xf bound_ctrl:1
	v_add_f32_dpp v114, v114, v114 row_ror:8 row_mask:0xf bank_mask:0xf bound_ctrl:1
	ds_read_b128 v[132:135], v95 offset:5888
	v_add_f32_dpp v112, v112, v112 row_ror:4 row_mask:0xf bank_mask:0xf bound_ctrl:1
	v_add_f32_dpp v114, v114, v114 row_ror:4 row_mask:0xf bank_mask:0xf bound_ctrl:1
	ds_read_b128 v[136:139], v95 offset:9984
	v_add_f32_dpp v112, v112, v112 row_ror:2 row_mask:0xf bank_mask:0xf bound_ctrl:1
	v_add_f32_dpp v114, v114, v114 row_ror:2 row_mask:0xf bank_mask:0xf bound_ctrl:1
	ds_read_b128 v[144:147], v95 offset:18176
	v_add_f32_dpp v112, v112, v112 row_ror:1 row_mask:0xf bank_mask:0xf bound_ctrl:1
	v_add_f32_dpp v114, v114, v114 row_ror:1 row_mask:0xf bank_mask:0xf bound_ctrl:1
	s_waitcnt lgkmcnt(8)
	v_pk_fma_f32 v[22:23], v[112:113], v[78:79], v[104:105] op_sel_hi:[0,1,1] neg_lo:[1,0,0] neg_hi:[1,0,0]
	v_pk_fma_f32 v[24:25], v[112:113], v[80:81], v[106:107] op_sel_hi:[0,1,1] neg_lo:[1,0,0] neg_hi:[1,0,0]
	ds_write_b32 v108, v114 offset:21824
	ds_read_b128 v[70:73], v95 offset:2048
	ds_read_b128 v[82:85], v95 offset:14336
	ds_read_b32 v100, v108 offset:20992
	s_waitcnt lgkmcnt(9)
	v_pk_mul_f32 v[102:103], v[22:23], v[128:129]
	s_waitcnt lgkmcnt(7)
	v_pk_mul_f32 v[104:105], v[140:141], v[148:149] op_sel_hi:[1,0]
	v_pk_fma_f32 v[102:103], v[24:25], v[130:131], v[102:103]
	v_pk_mul_f32 v[106:107], v[142:143], v[148:149] op_sel_hi:[1,0]
	v_pk_mul_f32 v[150:151], v[96:97], v[22:23]
	v_add_f32_e32 v112, v102, v103
	v_pk_fma_f32 v[150:151], v[98:99], v[24:25], v[150:151]
	s_waitcnt lgkmcnt(6)
	v_pk_fma_f32 v[104:105], v[22:23], v[132:133], v[104:105]
	v_add_f32_e32 v114, v150, v151
	v_pk_fma_f32 v[106:107], v[24:25], v[134:135], v[106:107]
	v_add_f32_dpp v112, v112, v112 row_ror:8 row_mask:0xf bank_mask:0xf bound_ctrl:1
	v_add_f32_dpp v114, v114, v114 row_ror:8 row_mask:0xf bank_mask:0xf bound_ctrl:1
	ds_read_b128 v[74:77], v95 offset:6144
	v_add_f32_dpp v112, v112, v112 row_ror:4 row_mask:0xf bank_mask:0xf bound_ctrl:1
	v_add_f32_dpp v114, v114, v114 row_ror:4 row_mask:0xf bank_mask:0xf bound_ctrl:1
	ds_read_b128 v[78:81], v95 offset:10240
	v_add_f32_dpp v112, v112, v112 row_ror:2 row_mask:0xf bank_mask:0xf bound_ctrl:1
	v_add_f32_dpp v114, v114, v114 row_ror:2 row_mask:0xf bank_mask:0xf bound_ctrl:1
	ds_read_b128 v[96:99], v95 offset:18432
	v_add_f32_dpp v112, v112, v112 row_ror:1 row_mask:0xf bank_mask:0xf bound_ctrl:1
	v_add_f32_dpp v114, v114, v114 row_ror:1 row_mask:0xf bank_mask:0xf bound_ctrl:1
	s_waitcnt lgkmcnt(8)
	v_pk_fma_f32 v[22:23], v[112:113], v[136:137], v[104:105] op_sel_hi:[0,1,1] neg_lo:[1,0,0] neg_hi:[1,0,0]
	v_pk_fma_f32 v[24:25], v[112:113], v[138:139], v[106:107] op_sel_hi:[0,1,1] neg_lo:[1,0,0] neg_hi:[1,0,0]
	ds_write_b32 v108, v114 offset:21888
	ds_read_b128 v[128:131], v95 offset:2304
	ds_read_b128 v[140:143], v95 offset:14592
	ds_read_b32 v148, v108 offset:21056
	s_waitcnt lgkmcnt(9)
	v_pk_mul_f32 v[102:103], v[22:23], v[70:71]
	s_waitcnt lgkmcnt(7)
	v_pk_mul_f32 v[104:105], v[82:83], v[100:101] op_sel_hi:[1,0]
	v_pk_fma_f32 v[102:103], v[24:25], v[72:73], v[102:103]
	v_pk_mul_f32 v[106:107], v[84:85], v[100:101] op_sel_hi:[1,0]
	v_pk_mul_f32 v[150:151], v[144:145], v[22:23]
	v_add_f32_e32 v112, v102, v103
	v_pk_fma_f32 v[150:151], v[146:147], v[24:25], v[150:151]
	s_waitcnt lgkmcnt(6)
	v_pk_fma_f32 v[104:105], v[22:23], v[74:75], v[104:105]
	v_add_f32_e32 v114, v150, v151
	v_pk_fma_f32 v[106:107], v[24:25], v[76:77], v[106:107]
	v_add_f32_dpp v112, v112, v112 row_ror:8 row_mask:0xf bank_mask:0xf bound_ctrl:1
	v_add_f32_dpp v114, v114, v114 row_ror:8 row_mask:0xf bank_mask:0xf bound_ctrl:1
	ds_read_b128 v[132:135], v95 offset:6400
	v_add_f32_dpp v112, v112, v112 row_ror:4 row_mask:0xf bank_mask:0xf bound_ctrl:1
	v_add_f32_dpp v114, v114, v114 row_ror:4 row_mask:0xf bank_mask:0xf bound_ctrl:1
	ds_read_b128 v[136:139], v95 offset:10496
	v_add_f32_dpp v112, v112, v112 row_ror:2 row_mask:0xf bank_mask:0xf bound_ctrl:1
	v_add_f32_dpp v114, v114, v114 row_ror:2 row_mask:0xf bank_mask:0xf bound_ctrl:1
	ds_read_b128 v[144:147], v95 offset:18688
	v_add_f32_dpp v112, v112, v112 row_ror:1 row_mask:0xf bank_mask:0xf bound_ctrl:1
	v_add_f32_dpp v114, v114, v114 row_ror:1 row_mask:0xf bank_mask:0xf bound_ctrl:1
	s_waitcnt lgkmcnt(8)
	v_pk_fma_f32 v[22:23], v[112:113], v[78:79], v[104:105] op_sel_hi:[0,1,1] neg_lo:[1,0,0] neg_hi:[1,0,0]
	v_pk_fma_f32 v[24:25], v[112:113], v[80:81], v[106:107] op_sel_hi:[0,1,1] neg_lo:[1,0,0] neg_hi:[1,0,0]
	ds_write_b32 v108, v114 offset:21952
	ds_read_b128 v[70:73], v95 offset:2560
	ds_read_b128 v[82:85], v95 offset:14848
	ds_read_b32 v100, v108 offset:21120
	s_waitcnt lgkmcnt(9)
	v_pk_mul_f32 v[102:103], v[22:23], v[128:129]
	s_waitcnt lgkmcnt(7)
	v_pk_mul_f32 v[104:105], v[140:141], v[148:149] op_sel_hi:[1,0]
	v_pk_fma_f32 v[102:103], v[24:25], v[130:131], v[102:103]
	v_pk_mul_f32 v[106:107], v[142:143], v[148:149] op_sel_hi:[1,0]
	v_pk_mul_f32 v[150:151], v[96:97], v[22:23]
	v_add_f32_e32 v112, v102, v103
	v_pk_fma_f32 v[150:151], v[98:99], v[24:25], v[150:151]
	s_waitcnt lgkmcnt(6)
	v_pk_fma_f32 v[104:105], v[22:23], v[132:133], v[104:105]
	v_add_f32_e32 v114, v150, v151
	v_pk_fma_f32 v[106:107], v[24:25], v[134:135], v[106:107]
	v_add_f32_dpp v112, v112, v112 row_ror:8 row_mask:0xf bank_mask:0xf bound_ctrl:1
	v_add_f32_dpp v114, v114, v114 row_ror:8 row_mask:0xf bank_mask:0xf bound_ctrl:1
	ds_read_b128 v[74:77], v95 offset:6656
	v_add_f32_dpp v112, v112, v112 row_ror:4 row_mask:0xf bank_mask:0xf bound_ctrl:1
	v_add_f32_dpp v114, v114, v114 row_ror:4 row_mask:0xf bank_mask:0xf bound_ctrl:1
	ds_read_b128 v[78:81], v95 offset:10752
	v_add_f32_dpp v112, v112, v112 row_ror:2 row_mask:0xf bank_mask:0xf bound_ctrl:1
	v_add_f32_dpp v114, v114, v114 row_ror:2 row_mask:0xf bank_mask:0xf bound_ctrl:1
	ds_read_b128 v[96:99], v95 offset:18944
	v_add_f32_dpp v112, v112, v112 row_ror:1 row_mask:0xf bank_mask:0xf bound_ctrl:1
	v_add_f32_dpp v114, v114, v114 row_ror:1 row_mask:0xf bank_mask:0xf bound_ctrl:1
	s_waitcnt lgkmcnt(8)
	v_pk_fma_f32 v[22:23], v[112:113], v[136:137], v[104:105] op_sel_hi:[0,1,1] neg_lo:[1,0,0] neg_hi:[1,0,0]
	v_pk_fma_f32 v[24:25], v[112:113], v[138:139], v[106:107] op_sel_hi:[0,1,1] neg_lo:[1,0,0] neg_hi:[1,0,0]
	ds_write_b32 v108, v114 offset:22016
	ds_read_b128 v[128:131], v95 offset:2816
	ds_read_b128 v[140:143], v95 offset:15104
	ds_read_b32 v148, v108 offset:21184
	s_waitcnt lgkmcnt(9)
	v_pk_mul_f32 v[102:103], v[22:23], v[70:71]
	s_waitcnt lgkmcnt(7)
	v_pk_mul_f32 v[104:105], v[82:83], v[100:101] op_sel_hi:[1,0]
	v_pk_fma_f32 v[102:103], v[24:25], v[72:73], v[102:103]
	v_pk_mul_f32 v[106:107], v[84:85], v[100:101] op_sel_hi:[1,0]
	v_pk_mul_f32 v[150:151], v[144:145], v[22:23]
	v_add_f32_e32 v112, v102, v103
	v_pk_fma_f32 v[150:151], v[146:147], v[24:25], v[150:151]
	s_waitcnt lgkmcnt(6)
	v_pk_fma_f32 v[104:105], v[22:23], v[74:75], v[104:105]
	v_add_f32_e32 v114, v150, v151
	v_pk_fma_f32 v[106:107], v[24:25], v[76:77], v[106:107]
	v_add_f32_dpp v112, v112, v112 row_ror:8 row_mask:0xf bank_mask:0xf bound_ctrl:1
	v_add_f32_dpp v114, v114, v114 row_ror:8 row_mask:0xf bank_mask:0xf bound_ctrl:1
	ds_read_b128 v[132:135], v95 offset:6912
	v_add_f32_dpp v112, v112, v112 row_ror:4 row_mask:0xf bank_mask:0xf bound_ctrl:1
	v_add_f32_dpp v114, v114, v114 row_ror:4 row_mask:0xf bank_mask:0xf bound_ctrl:1
	ds_read_b128 v[136:139], v95 offset:11008
	v_add_f32_dpp v112, v112, v112 row_ror:2 row_mask:0xf bank_mask:0xf bound_ctrl:1
	v_add_f32_dpp v114, v114, v114 row_ror:2 row_mask:0xf bank_mask:0xf bound_ctrl:1
	ds_read_b128 v[144:147], v95 offset:19200
	v_add_f32_dpp v112, v112, v112 row_ror:1 row_mask:0xf bank_mask:0xf bound_ctrl:1
	v_add_f32_dpp v114, v114, v114 row_ror:1 row_mask:0xf bank_mask:0xf bound_ctrl:1
	s_waitcnt lgkmcnt(8)
	v_pk_fma_f32 v[22:23], v[112:113], v[78:79], v[104:105] op_sel_hi:[0,1,1] neg_lo:[1,0,0] neg_hi:[1,0,0]
	v_pk_fma_f32 v[24:25], v[112:113], v[80:81], v[106:107] op_sel_hi:[0,1,1] neg_lo:[1,0,0] neg_hi:[1,0,0]
	ds_write_b32 v108, v114 offset:22080
	ds_read_b128 v[70:73], v95 offset:3072
	ds_read_b128 v[82:85], v95 offset:15360
	ds_read_b32 v100, v108 offset:21248
	s_waitcnt lgkmcnt(9)
	v_pk_mul_f32 v[102:103], v[22:23], v[128:129]
	s_waitcnt lgkmcnt(7)
	v_pk_mul_f32 v[104:105], v[140:141], v[148:149] op_sel_hi:[1,0]
	v_pk_fma_f32 v[102:103], v[24:25], v[130:131], v[102:103]
	v_pk_mul_f32 v[106:107], v[142:143], v[148:149] op_sel_hi:[1,0]
	v_pk_mul_f32 v[150:151], v[96:97], v[22:23]
	v_add_f32_e32 v112, v102, v103
	v_pk_fma_f32 v[150:151], v[98:99], v[24:25], v[150:151]
	s_waitcnt lgkmcnt(6)
	v_pk_fma_f32 v[104:105], v[22:23], v[132:133], v[104:105]
	v_add_f32_e32 v114, v150, v151
	v_pk_fma_f32 v[106:107], v[24:25], v[134:135], v[106:107]
	v_add_f32_dpp v112, v112, v112 row_ror:8 row_mask:0xf bank_mask:0xf bound_ctrl:1
	v_add_f32_dpp v114, v114, v114 row_ror:8 row_mask:0xf bank_mask:0xf bound_ctrl:1
	ds_read_b128 v[74:77], v95 offset:7168
	v_add_f32_dpp v112, v112, v112 row_ror:4 row_mask:0xf bank_mask:0xf bound_ctrl:1
	v_add_f32_dpp v114, v114, v114 row_ror:4 row_mask:0xf bank_mask:0xf bound_ctrl:1
	ds_read_b128 v[78:81], v95 offset:11264
	v_add_f32_dpp v112, v112, v112 row_ror:2 row_mask:0xf bank_mask:0xf bound_ctrl:1
	v_add_f32_dpp v114, v114, v114 row_ror:2 row_mask:0xf bank_mask:0xf bound_ctrl:1
	ds_read_b128 v[96:99], v95 offset:19456
	v_add_f32_dpp v112, v112, v112 row_ror:1 row_mask:0xf bank_mask:0xf bound_ctrl:1
	v_add_f32_dpp v114, v114, v114 row_ror:1 row_mask:0xf bank_mask:0xf bound_ctrl:1
	s_waitcnt lgkmcnt(8)
	v_pk_fma_f32 v[22:23], v[112:113], v[136:137], v[104:105] op_sel_hi:[0,1,1] neg_lo:[1,0,0] neg_hi:[1,0,0]
	v_pk_fma_f32 v[24:25], v[112:113], v[138:139], v[106:107] op_sel_hi:[0,1,1] neg_lo:[1,0,0] neg_hi:[1,0,0]
	ds_write_b32 v108, v114 offset:22144
	ds_read_b128 v[128:131], v95 offset:3328
	ds_read_b128 v[140:143], v95 offset:15616
	ds_read_b32 v148, v108 offset:21312
	s_waitcnt lgkmcnt(9)
	v_pk_mul_f32 v[102:103], v[22:23], v[70:71]
	s_waitcnt lgkmcnt(7)
	v_pk_mul_f32 v[104:105], v[82:83], v[100:101] op_sel_hi:[1,0]
	v_pk_fma_f32 v[102:103], v[24:25], v[72:73], v[102:103]
	v_pk_mul_f32 v[106:107], v[84:85], v[100:101] op_sel_hi:[1,0]
	v_pk_mul_f32 v[150:151], v[144:145], v[22:23]
	v_add_f32_e32 v112, v102, v103
	v_pk_fma_f32 v[150:151], v[146:147], v[24:25], v[150:151]
	s_waitcnt lgkmcnt(6)
	v_pk_fma_f32 v[104:105], v[22:23], v[74:75], v[104:105]
	v_add_f32_e32 v114, v150, v151
	v_pk_fma_f32 v[106:107], v[24:25], v[76:77], v[106:107]
	v_add_f32_dpp v112, v112, v112 row_ror:8 row_mask:0xf bank_mask:0xf bound_ctrl:1
	v_add_f32_dpp v114, v114, v114 row_ror:8 row_mask:0xf bank_mask:0xf bound_ctrl:1
	ds_read_b128 v[132:135], v95 offset:7424
	v_add_f32_dpp v112, v112, v112 row_ror:4 row_mask:0xf bank_mask:0xf bound_ctrl:1
	v_add_f32_dpp v114, v114, v114 row_ror:4 row_mask:0xf bank_mask:0xf bound_ctrl:1
	ds_read_b128 v[136:139], v95 offset:11520
	v_add_f32_dpp v112, v112, v112 row_ror:2 row_mask:0xf bank_mask:0xf bound_ctrl:1
	v_add_f32_dpp v114, v114, v114 row_ror:2 row_mask:0xf bank_mask:0xf bound_ctrl:1
	ds_read_b128 v[144:147], v95 offset:19712
	v_add_f32_dpp v112, v112, v112 row_ror:1 row_mask:0xf bank_mask:0xf bound_ctrl:1
	v_add_f32_dpp v114, v114, v114 row_ror:1 row_mask:0xf bank_mask:0xf bound_ctrl:1
	s_waitcnt lgkmcnt(8)
	v_pk_fma_f32 v[22:23], v[112:113], v[78:79], v[104:105] op_sel_hi:[0,1,1] neg_lo:[1,0,0] neg_hi:[1,0,0]
	v_pk_fma_f32 v[24:25], v[112:113], v[80:81], v[106:107] op_sel_hi:[0,1,1] neg_lo:[1,0,0] neg_hi:[1,0,0]
	ds_write_b32 v108, v114 offset:22208
	ds_read_b128 v[70:73], v95 offset:3584
	ds_read_b128 v[82:85], v95 offset:15872
	ds_read_b32 v100, v108 offset:21376
	s_waitcnt lgkmcnt(9)
	v_pk_mul_f32 v[102:103], v[22:23], v[128:129]
	s_waitcnt lgkmcnt(7)
	v_pk_mul_f32 v[104:105], v[140:141], v[148:149] op_sel_hi:[1,0]
	v_pk_fma_f32 v[102:103], v[24:25], v[130:131], v[102:103]
	v_pk_mul_f32 v[106:107], v[142:143], v[148:149] op_sel_hi:[1,0]
	v_pk_mul_f32 v[150:151], v[96:97], v[22:23]
	v_add_f32_e32 v112, v102, v103
	v_pk_fma_f32 v[150:151], v[98:99], v[24:25], v[150:151]
	s_waitcnt lgkmcnt(6)
	v_pk_fma_f32 v[104:105], v[22:23], v[132:133], v[104:105]
	v_add_f32_e32 v114, v150, v151
	v_pk_fma_f32 v[106:107], v[24:25], v[134:135], v[106:107]
	v_add_f32_dpp v112, v112, v112 row_ror:8 row_mask:0xf bank_mask:0xf bound_ctrl:1
	v_add_f32_dpp v114, v114, v114 row_ror:8 row_mask:0xf bank_mask:0xf bound_ctrl:1
	ds_read_b128 v[74:77], v95 offset:7680
	v_add_f32_dpp v112, v112, v112 row_ror:4 row_mask:0xf bank_mask:0xf bound_ctrl:1
	v_add_f32_dpp v114, v114, v114 row_ror:4 row_mask:0xf bank_mask:0xf bound_ctrl:1
	ds_read_b128 v[78:81], v95 offset:11776
	v_add_f32_dpp v112, v112, v112 row_ror:2 row_mask:0xf bank_mask:0xf bound_ctrl:1
	v_add_f32_dpp v114, v114, v114 row_ror:2 row_mask:0xf bank_mask:0xf bound_ctrl:1
	ds_read_b128 v[96:99], v95 offset:19968
	v_add_f32_dpp v112, v112, v112 row_ror:1 row_mask:0xf bank_mask:0xf bound_ctrl:1
	v_add_f32_dpp v114, v114, v114 row_ror:1 row_mask:0xf bank_mask:0xf bound_ctrl:1
	s_waitcnt lgkmcnt(8)
	v_pk_fma_f32 v[22:23], v[112:113], v[136:137], v[104:105] op_sel_hi:[0,1,1] neg_lo:[1,0,0] neg_hi:[1,0,0]
	v_pk_fma_f32 v[24:25], v[112:113], v[138:139], v[106:107] op_sel_hi:[0,1,1] neg_lo:[1,0,0] neg_hi:[1,0,0]
	ds_write_b32 v108, v114 offset:22272
	ds_read_b128 v[128:131], v95 offset:3840
	ds_read_b128 v[140:143], v95 offset:16128
	ds_read_b32 v148, v108 offset:21440
	s_waitcnt lgkmcnt(9)
	v_pk_mul_f32 v[102:103], v[22:23], v[70:71]
	s_waitcnt lgkmcnt(7)
	v_pk_mul_f32 v[104:105], v[82:83], v[100:101] op_sel_hi:[1,0]
	v_pk_fma_f32 v[102:103], v[24:25], v[72:73], v[102:103]
	v_pk_mul_f32 v[106:107], v[84:85], v[100:101] op_sel_hi:[1,0]
	v_pk_mul_f32 v[150:151], v[144:145], v[22:23]
	v_add_f32_e32 v112, v102, v103
	v_pk_fma_f32 v[150:151], v[146:147], v[24:25], v[150:151]
	s_waitcnt lgkmcnt(6)
	v_pk_fma_f32 v[104:105], v[22:23], v[74:75], v[104:105]
	v_add_f32_e32 v114, v150, v151
	v_pk_fma_f32 v[106:107], v[24:25], v[76:77], v[106:107]
	v_add_f32_dpp v112, v112, v112 row_ror:8 row_mask:0xf bank_mask:0xf bound_ctrl:1
	v_add_f32_dpp v114, v114, v114 row_ror:8 row_mask:0xf bank_mask:0xf bound_ctrl:1
	ds_read_b128 v[132:135], v95 offset:7936
	v_add_f32_dpp v112, v112, v112 row_ror:4 row_mask:0xf bank_mask:0xf bound_ctrl:1
	v_add_f32_dpp v114, v114, v114 row_ror:4 row_mask:0xf bank_mask:0xf bound_ctrl:1
	ds_read_b128 v[136:139], v95 offset:12032
	v_add_f32_dpp v112, v112, v112 row_ror:2 row_mask:0xf bank_mask:0xf bound_ctrl:1
	v_add_f32_dpp v114, v114, v114 row_ror:2 row_mask:0xf bank_mask:0xf bound_ctrl:1
	ds_read_b128 v[144:147], v95 offset:20224
	v_add_f32_dpp v112, v112, v112 row_ror:1 row_mask:0xf bank_mask:0xf bound_ctrl:1
	v_add_f32_dpp v114, v114, v114 row_ror:1 row_mask:0xf bank_mask:0xf bound_ctrl:1
	s_waitcnt lgkmcnt(8)
	v_pk_fma_f32 v[22:23], v[112:113], v[78:79], v[104:105] op_sel_hi:[0,1,1] neg_lo:[1,0,0] neg_hi:[1,0,0]
	v_pk_fma_f32 v[24:25], v[112:113], v[80:81], v[106:107] op_sel_hi:[0,1,1] neg_lo:[1,0,0] neg_hi:[1,0,0]
	ds_write_b32 v108, v114 offset:22336
	s_waitcnt lgkmcnt(6)
	v_pk_mul_f32 v[102:103], v[22:23], v[128:129]
	s_waitcnt lgkmcnt(4)
	v_pk_mul_f32 v[104:105], v[140:141], v[148:149] op_sel_hi:[1,0]
	v_pk_fma_f32 v[102:103], v[24:25], v[130:131], v[102:103]
	v_pk_mul_f32 v[106:107], v[142:143], v[148:149] op_sel_hi:[1,0]
	v_pk_mul_f32 v[150:151], v[96:97], v[22:23]
	v_add_f32_e32 v112, v102, v103
	v_pk_fma_f32 v[150:151], v[98:99], v[24:25], v[150:151]
	s_waitcnt lgkmcnt(3)
	v_pk_fma_f32 v[104:105], v[22:23], v[132:133], v[104:105]
	v_add_f32_e32 v114, v150, v151
	v_pk_fma_f32 v[106:107], v[24:25], v[134:135], v[106:107]
	v_add_f32_dpp v112, v112, v112 row_ror:8 row_mask:0xf bank_mask:0xf bound_ctrl:1
	v_add_f32_dpp v114, v114, v114 row_ror:8 row_mask:0xf bank_mask:0xf bound_ctrl:1
	s_nop 0
	v_add_f32_dpp v112, v112, v112 row_ror:4 row_mask:0xf bank_mask:0xf bound_ctrl:1
	s_nop 0
	v_add_f32_dpp v114, v114, v114 row_ror:4 row_mask:0xf bank_mask:0xf bound_ctrl:1
	s_nop 0
	v_add_f32_dpp v112, v112, v112 row_ror:2 row_mask:0xf bank_mask:0xf bound_ctrl:1
	s_nop 0
	v_add_f32_dpp v114, v114, v114 row_ror:2 row_mask:0xf bank_mask:0xf bound_ctrl:1
	s_nop 0
	v_add_f32_dpp v112, v112, v112 row_ror:1 row_mask:0xf bank_mask:0xf bound_ctrl:1
	s_nop 0
	v_add_f32_dpp v114, v114, v114 row_ror:1 row_mask:0xf bank_mask:0xf bound_ctrl:1
	s_waitcnt lgkmcnt(2)
	v_pk_fma_f32 v[22:23], v[112:113], v[136:137], v[104:105] op_sel_hi:[0,1,1] neg_lo:[1,0,0] neg_hi:[1,0,0]
	v_pk_fma_f32 v[24:25], v[112:113], v[138:139], v[106:107] op_sel_hi:[0,1,1] neg_lo:[1,0,0] neg_hi:[1,0,0]
	ds_write_b32 v108, v114 offset:22400
	s_waitcnt lgkmcnt(2)
	v_pk_mul_f32 v[150:151], v[144:145], v[22:23]
	v_pk_fma_f32 v[150:151], v[146:147], v[24:25], v[150:151]
	v_add_f32_e32 v114, v150, v151
	s_nop 1
	v_add_f32_dpp v114, v114, v114 row_ror:8 row_mask:0xf bank_mask:0xf bound_ctrl:1
	s_nop 1
	v_add_f32_dpp v114, v114, v114 row_ror:4 row_mask:0xf bank_mask:0xf bound_ctrl:1
	s_nop 1
	v_add_f32_dpp v114, v114, v114 row_ror:2 row_mask:0xf bank_mask:0xf bound_ctrl:1
	s_nop 1
	v_add_f32_dpp v114, v114, v114 row_ror:1 row_mask:0xf bank_mask:0xf bound_ctrl:1
	ds_write_b32 v108, v114 offset:22464
	s_add_u32 s28, s28, 16
	s_mov_b32 s35, 1
	s_waitcnt vmcnt(0)
	ds_write_b128 v110, v[58:61] offset:23552
	ds_write_b128 v110, v[62:65] offset:27648
	ds_write_b128 v110, v[66:69] offset:31744
	s_waitcnt lgkmcnt(0)
	s_barrier
	s_add_u32 s30, s28, 32
	v_add_u32_e32 v87, s30, v15
	v_med3_i32 v87, v87, 0, s29
	v_mad_i64_i32 v[104:105], vcc, v87, v12, v[6:7]
	global_load_dwordx4 v[58:61], v[104:105], off
	v_add_u32_e32 v87, s30, v16
	v_med3_i32 v87, v87, 0, s29
	v_mad_i64_i32 v[104:105], vcc, v87, v13, v[8:9]
	global_load_dwordx4 v[62:65], v[104:105], off
	v_add_u32_e32 v87, s30, v17
	v_med3_i32 v87, v87, 0, s29
	v_mad_i64_i32 v[104:105], vcc, v87, v14, v[10:11]
	global_load_dwordx4 v[66:69], v[104:105], off
	ds_read_b32 v89, v115 offset:21504
	s_sub_u32 s98, s28, 16
	v_add_u32_e32 v87, s98, v127
	v_mad_i64_i32 v[104:105], vcc, v87, v20, v[18:19]
	s_waitcnt lgkmcnt(0)
	v_cvt_pk_bf16_f32 v89, v89, v89
	global_store_short v[104:105], v89, off
	ds_read_b64 v[70:71], v1 offset:23936
	ds_read_b64 v[72:73], v1 offset:23552
	ds_read_b64 v[74:75], v1 offset:24320
	ds_read_b64 v[76:77], v1 offset:24064
	ds_read_b64 v[78:79], v1 offset:23680
	ds_read_b64 v[80:81], v1 offset:24448
	ds_read_b64 v[82:83], v1 offset:24192
	ds_read_b64 v[84:85], v1 offset:23808
	ds_read_b64 v[96:97], v1 offset:24576
	ds_read_b64 v[128:129], v2 offset:30464
	ds_read_b64 v[130:131], v2 offset:30592
	v_add_u32_e32 v87, s28, v127
	v_cmp_ne_u32_e32 vcc, 0, v87
	s_nop 1
	v_cndmask_b32_e64 v98, 0, 0.5, vcc
	v_cmp_ne_u32_e32 vcc, s29, v87
	s_nop 1
	v_cndmask_b32_e64 v100, 0, 0.5, vcc
	s_waitcnt lgkmcnt(8)
	v_lshlrev_b32_e32 v132, 16, v70
	v_and_b32_e32 v133, 0xffff0000, v70
	v_lshlrev_b32_e32 v134, 16, v71
	v_and_b32_e32 v135, 0xffff0000, v71
	v_lshlrev_b32_e32 v136, 16, v72
	v_and_b32_e32 v137, 0xffff0000, v72
	v_lshlrev_b32_e32 v138, 16, v73
	v_and_b32_e32 v139, 0xffff0000, v73
	v_lshlrev_b32_e32 v140, 16, v74
	v_and_b32_e32 v141, 0xffff0000, v74
	v_lshlrev_b32_e32 v142, 16, v75
	v_and_b32_e32 v143, 0xffff0000, v75
	v_pk_mul_f32 v[136:137], v[136:137], v[98:99] op_sel_hi:[1,0]
	v_pk_fma_f32 v[136:137], v[140:141], v[100:101], v[136:137] op_sel_hi:[1,0,1]
	v_pk_add_f32 v[136:137], v[136:137], v[132:133] neg_lo:[0,1] neg_hi:[0,1]
	v_pk_fma_f32 v[144:145], v[26:27], v[136:137], v[132:133]
	v_pk_mul_f32 v[138:139], v[138:139], v[98:99] op_sel_hi:[1,0]
	v_pk_fma_f32 v[138:139], v[142:143], v[100:101], v[138:139] op_sel_hi:[1,0,1]
	v_pk_add_f32 v[138:139], v[138:139], v[134:135] neg_lo:[0,1] neg_hi:[0,1]
	v_pk_fma_f32 v[146:147], v[28:29], v[138:139], v[134:135]
	s_waitcnt lgkmcnt(5)
	v_lshlrev_b32_e32 v132, 16, v76
	v_and_b32_e32 v133, 0xffff0000, v76
	v_lshlrev_b32_e32 v134, 16, v77
	v_and_b32_e32 v135, 0xffff0000, v77
	v_lshlrev_b32_e32 v136, 16, v78
	v_and_b32_e32 v137, 0xffff0000, v78
	v_lshlrev_b32_e32 v138, 16, v79
	v_and_b32_e32 v139, 0xffff0000, v79
	v_lshlrev_b32_e32 v140, 16, v80
	v_and_b32_e32 v141, 0xffff0000, v80
	v_lshlrev_b32_e32 v142, 16, v81
	v_and_b32_e32 v143, 0xffff0000, v81
	v_pk_mul_f32 v[136:137], v[136:137], v[98:99] op_sel_hi:[1,0]
	v_pk_fma_f32 v[136:137], v[140:141], v[100:101], v[136:137] op_sel_hi:[1,0,1]
	v_pk_add_f32 v[136:137], v[136:137], v[132:133] neg_lo:[0,1] neg_hi:[0,1]
	v_pk_fma_f32 v[102:103], v[30:31], v[136:137], v[132:133]
	v_pk_mul_f32 v[138:139], v[138:139], v[98:99] op_sel_hi:[1,0]
	v_pk_fma_f32 v[138:139], v[142:143], v[100:101], v[138:139] op_sel_hi:[1,0,1]
	v_pk_add_f32 v[138:139], v[138:139], v[134:135] neg_lo:[0,1] neg_hi:[0,1]
	v_pk_fma_f32 v[104:105], v[32:33], v[138:139], v[134:135]
	s_waitcnt lgkmcnt(2)
	v_lshlrev_b32_e32 v132, 16, v82
	v_and_b32_e32 v133, 0xffff0000, v82
	v_lshlrev_b32_e32 v134, 16, v83
	v_and_b32_e32 v135, 0xffff0000, v83
	v_lshlrev_b32_e32 v136, 16, v84
	v_and_b32_e32 v137, 0xffff0000, v84
	v_lshlrev_b32_e32 v138, 16, v85
	v_and_b32_e32 v139, 0xffff0000, v85
	v_lshlrev_b32_e32 v140, 16, v96
	v_and_b32_e32 v141, 0xffff0000, v96
	v_lshlrev_b32_e32 v142, 16, v97
	v_and_b32_e32 v143, 0xffff0000, v97
	v_pk_mul_f32 v[136:137], v[136:137], v[98:99] op_sel_hi:[1,0]
	v_pk_fma_f32 v[136:137], v[140:141], v[100:101], v[136:137] op_sel_hi:[1,0,1]
	v_pk_add_f32 v[136:137], v[136:137], v[132:133] neg_lo:[0,1] neg_hi:[0,1]
	v_pk_fma_f32 v[148:149], v[34:35], v[136:137], v[132:133]
	v_pk_mul_f32 v[138:139], v[138:139], v[98:99] op_sel_hi:[1,0]
	v_pk_fma_f32 v[138:139], v[142:143], v[100:101], v[138:139] op_sel_hi:[1,0,1]
	v_pk_add_f32 v[138:139], v[138:139], v[134:135] neg_lo:[0,1] neg_hi:[0,1]
	v_pk_fma_f32 v[150:151], v[36:37], v[138:139], v[134:135]
	s_waitcnt lgkmcnt(0)
	v_lshlrev_b32_e32 v132, 16, v128
	v_and_b32_e32 v133, 0xffff0000, v128
	v_lshlrev_b32_e32 v134, 16, v129
	v_and_b32_e32 v135, 0xffff0000, v129
	v_lshlrev_b32_e32 v136, 16, v130
	v_and_b32_e32 v137, 0xffff0000, v130
	v_lshlrev_b32_e32 v138, 16, v131
	v_and_b32_e32 v139, 0xffff0000, v131
	s_mov_b32 s98, 0xbf60028b
	v_mul_f32_e32 v132, s98, v132
	v_mul_f32_e32 v133, s98, v133
	v_mul_f32_e32 v134, s98, v134
	v_mul_f32_e32 v135, s98, v135
	v_exp_f32_e32 v132, v132
	v_exp_f32_e32 v133, v133
	v_exp_f32_e32 v134, v134
	v_exp_f32_e32 v135, v135
	v_pk_mul_f32 v[140:141], v[102:103], v[38:39]
	v_pk_mul_f32 v[142:143], v[104:105], v[40:41]
	v_pk_mul_f32 v[106:107], v[140:141], v[140:141]
	v_pk_fma_f32 v[106:107], v[142:143], v[142:143], v[106:107]
	v_add_f32_e32 v106, v106, v107
	s_nop 1
	v_add_f32_dpp v106, v106, v106 row_ror:8 row_mask:0xf bank_mask:0xf bound_ctrl:1
	s_nop 1
	v_add_f32_dpp v106, v106, v106 row_ror:4 row_mask:0xf bank_mask:0xf bound_ctrl:1
	s_nop 1
	v_add_f32_dpp v106, v106, v106 row_ror:2 row_mask:0xf bank_mask:0xf bound_ctrl:1
	s_nop 1
	v_add_f32_dpp v106, v106, v106 row_ror:1 row_mask:0xf bank_mask:0xf bound_ctrl:1
	v_add_f32_e32 v106, 0x2b8cbccc, v106
	v_rsq_f32_e32 v106, v106
	v_pk_mul_f32 v[148:149], v[148:149], s[40:41] op_sel_hi:[1,0]
	v_pk_mul_f32 v[150:151], v[150:151], s[40:41] op_sel_hi:[1,0]
	v_pk_mul_f32 v[140:141], v[140:141], v[106:107] op_sel_hi:[1,0]
	v_pk_mul_f32 v[142:143], v[142:143], v[106:107] op_sel_hi:[1,0]
	v_pk_add_f32 v[70:71], v[136:137], -1.0 op_sel_hi:[1,0]
	v_pk_add_f32 v[72:73], v[138:139], -1.0 op_sel_hi:[1,0]
	v_pk_fma_f32 v[70:71], v[42:43], v[70:71], 1.0 op_sel_hi:[1,1,0]
	v_pk_fma_f32 v[72:73], v[44:45], v[72:73], 1.0 op_sel_hi:[1,1,0]
	v_pk_mul_f32 v[70:71], v[102:103], v[70:71]
	v_pk_mul_f32 v[72:73], v[104:105], v[72:73]
	v_pk_mul_f32 v[74:75], v[140:141], v[136:137]
	v_pk_mul_f32 v[76:77], v[142:143], v[138:139]
	ds_write_b128 v3, v[140:143] offset:0
	ds_write_b128 v3, v[132:135] offset:4096
	ds_write_b128 v3, v[74:77] offset:8192
	ds_write_b128 v3, v[70:73] offset:12288
	ds_write_b128 v3, v[144:147] offset:16384
	ds_write_b128 v4, v[148:151]
	s_waitcnt lgkmcnt(0)
	s_barrier
	ds_read_b128 v[70:73], v95 offset:0
	ds_read_b128 v[82:85], v95 offset:12288
	ds_read_b32 v100, v108 offset:20480
	ds_read_b128 v[74:77], v95 offset:4096
	ds_read_b128 v[78:81], v95 offset:8192
	ds_read_b128 v[96:99], v95 offset:16384
	ds_read_b128 v[128:131], v95 offset:256
	ds_read_b128 v[140:143], v95 offset:12544
	ds_read_b32 v148, v108 offset:20544
	s_waitcnt lgkmcnt(8)
	v_pk_mul_f32 v[102:103], v[22:23], v[70:71]
	s_waitcnt lgkmcnt(6)
	v_pk_mul_f32 v[104:105], v[82:83], v[100:101] op_sel_hi:[1,0]
	v_pk_fma_f32 v[102:103], v[24:25], v[72:73], v[102:103]
	v_pk_mul_f32 v[106:107], v[84:85], v[100:101] op_sel_hi:[1,0]
	v_add_f32_e32 v112, v102, v103
	s_waitcnt lgkmcnt(5)
	v_pk_fma_f32 v[104:105], v[22:23], v[74:75], v[104:105]
	v_pk_fma_f32 v[106:107], v[24:25], v[76:77], v[106:107]
	v_add_f32_dpp v112, v112, v112 row_ror:8 row_mask:0xf bank_mask:0xf bound_ctrl:1
	ds_read_b128 v[132:135], v95 offset:4352
	s_nop 0
	v_add_f32_dpp v112, v112, v112 row_ror:4 row_mask:0xf bank_mask:0xf bound_ctrl:1
	ds_read_b128 v[136:139], v95 offset:8448
	s_nop 0
	v_add_f32_dpp v112, v112, v112 row_ror:2 row_mask:0xf bank_mask:0xf bound_ctrl:1
	ds_read_b128 v[144:147], v95 offset:16640
	s_nop 0
	v_add_f32_dpp v112, v112, v112 row_ror:1 row_mask:0xf bank_mask:0xf bound_ctrl:1
	s_waitcnt lgkmcnt(7)
	v_pk_fma_f32 v[22:23], v[112:113], v[78:79], v[104:105] op_sel_hi:[0,1,1] neg_lo:[1,0,0] neg_hi:[1,0,0]
	v_pk_fma_f32 v[24:25], v[112:113], v[80:81], v[106:107] op_sel_hi:[0,1,1] neg_lo:[1,0,0] neg_hi:[1,0,0]
	ds_read_b128 v[70:73], v95 offset:512
	ds_read_b128 v[82:85], v95 offset:12800
	ds_read_b32 v100, v108 offset:20608
	s_waitcnt lgkmcnt(8)
	v_pk_mul_f32 v[102:103], v[22:23], v[128:129]
	s_waitcnt lgkmcnt(6)
	v_pk_mul_f32 v[104:105], v[140:141], v[148:149] op_sel_hi:[1,0]
	v_pk_fma_f32 v[102:103], v[24:25], v[130:131], v[102:103]
	v_pk_mul_f32 v[106:107], v[142:143], v[148:149] op_sel_hi:[1,0]
	v_pk_mul_f32 v[150:151], v[96:97], v[22:23]
	v_add_f32_e32 v112, v102, v103
	v_pk_fma_f32 v[150:151], v[98:99], v[24:25], v[150:151]
	s_waitcnt lgkmcnt(5)
	v_pk_fma_f32 v[104:105], v[22:23], v[132:133], v[104:105]
	v_add_f32_e32 v114, v150, v151
	v_pk_fma_f32 v[106:107], v[24:25], v[134:135], v[106:107]
	v_add_f32_dpp v112, v112, v112 row_ror:8 row_mask:0xf bank_mask:0xf bound_ctrl:1
	v_add_f32_dpp v114, v114, v114 row_ror:8 row_mask:0xf bank_mask:0xf bound_ctrl:1
	ds_read_b128 v[74:77], v95 offset:4608
	v_add_f32_dpp v112, v112, v112 row_ror:4 row_mask:0xf bank_mask:0xf bound_ctrl:1
	v_add_f32_dpp v114, v114, v114 row_ror:4 row_mask:0xf bank_mask:0xf bound_ctrl:1
	ds_read_b128 v[78:81], v95 offset:8704
	v_add_f32_dpp v112, v112, v112 row_ror:2 row_mask:0xf bank_mask:0xf bound_ctrl:1
	v_add_f32_dpp v114, v114, v114 row_ror:2 row_mask:0xf bank_mask:0xf bound_ctrl:1
	ds_read_b128 v[96:99], v95 offset:16896
	v_add_f32_dpp v112, v112, v112 row_ror:1 row_mask:0xf bank_mask:0xf bound_ctrl:1
	v_add_f32_dpp v114, v114, v114 row_ror:1 row_mask:0xf bank_mask:0xf bound_ctrl:1
	s_waitcnt lgkmcnt(7)
	v_pk_fma_f32 v[22:23], v[112:113], v[136:137], v[104:105] op_sel_hi:[0,1,1] neg_lo:[1,0,0] neg_hi:[1,0,0]
	v_pk_fma_f32 v[24:25], v[112:113], v[138:139], v[106:107] op_sel_hi:[0,1,1] neg_lo:[1,0,0] neg_hi:[1,0,0]
	ds_write_b32 v108, v114 offset:22528
	ds_read_b128 v[128:131], v95 offset:768
	ds_read_b128 v[140:143], v95 offset:13056
	ds_read_b32 v148, v108 offset:20672
	s_waitcnt lgkmcnt(9)
	v_pk_mul_f32 v[102:103], v[22:23], v[70:71]
	s_waitcnt lgkmcnt(7)
	v_pk_mul_f32 v[104:105], v[82:83], v[100:101] op_sel_hi:[1,0]
	v_pk_fma_f32 v[102:103], v[24:25], v[72:73], v[102:103]
	v_pk_mul_f32 v[106:107], v[84:85], v[100:101] op_sel_hi:[1,0]
	v_pk_mul_f32 v[150:151], v[144:145], v[22:23]
	v_add_f32_e32 v112, v102, v103
	v_pk_fma_f32 v[150:151], v[146:147], v[24:25], v[150:151]
	s_waitcnt lgkmcnt(6)
	v_pk_fma_f32 v[104:105], v[22:23], v[74:75], v[104:105]
	v_add_f32_e32 v114, v150, v151
	v_pk_fma_f32 v[106:107], v[24:25], v[76:77], v[106:107]
	v_add_f32_dpp v112, v112, v112 row_ror:8 row_mask:0xf bank_mask:0xf bound_ctrl:1
	v_add_f32_dpp v114, v114, v114 row_ror:8 row_mask:0xf bank_mask:0xf bound_ctrl:1
	ds_read_b128 v[132:135], v95 offset:4864
	v_add_f32_dpp v112, v112, v112 row_ror:4 row_mask:0xf bank_mask:0xf bound_ctrl:1
	v_add_f32_dpp v114, v114, v114 row_ror:4 row_mask:0xf bank_mask:0xf bound_ctrl:1
	ds_read_b128 v[136:139], v95 offset:8960
	v_add_f32_dpp v112, v112, v112 row_ror:2 row_mask:0xf bank_mask:0xf bound_ctrl:1
	v_add_f32_dpp v114, v114, v114 row_ror:2 row_mask:0xf bank_mask:0xf bound_ctrl:1
	ds_read_b128 v[144:147], v95 offset:17152
	v_add_f32_dpp v112, v112, v112 row_ror:1 row_mask:0xf bank_mask:0xf bound_ctrl:1
	v_add_f32_dpp v114, v114, v114 row_ror:1 row_mask:0xf bank_mask:0xf bound_ctrl:1
	s_waitcnt lgkmcnt(8)
	v_pk_fma_f32 v[22:23], v[112:113], v[78:79], v[104:105] op_sel_hi:[0,1,1] neg_lo:[1,0,0] neg_hi:[1,0,0]
	v_pk_fma_f32 v[24:25], v[112:113], v[80:81], v[106:107] op_sel_hi:[0,1,1] neg_lo:[1,0,0] neg_hi:[1,0,0]
	ds_write_b32 v108, v114 offset:22592
	ds_read_b128 v[70:73], v95 offset:1024
	ds_read_b128 v[82:85], v95 offset:13312
	ds_read_b32 v100, v108 offset:20736
	s_waitcnt lgkmcnt(9)
	v_pk_mul_f32 v[102:103], v[22:23], v[128:129]
	s_waitcnt lgkmcnt(7)
	v_pk_mul_f32 v[104:105], v[140:141], v[148:149] op_sel_hi:[1,0]
	v_pk_fma_f32 v[102:103], v[24:25], v[130:131], v[102:103]
	v_pk_mul_f32 v[106:107], v[142:143], v[148:149] op_sel_hi:[1,0]
	v_pk_mul_f32 v[150:151], v[96:97], v[22:23]
	v_add_f32_e32 v112, v102, v103
	v_pk_fma_f32 v[150:151], v[98:99], v[24:25], v[150:151]
	s_waitcnt lgkmcnt(6)
	v_pk_fma_f32 v[104:105], v[22:23], v[132:133], v[104:105]
	v_add_f32_e32 v114, v150, v151
	v_pk_fma_f32 v[106:107], v[24:25], v[134:135], v[106:107]
	v_add_f32_dpp v112, v112, v112 row_ror:8 row_mask:0xf bank_mask:0xf bound_ctrl:1
	v_add_f32_dpp v114, v114, v114 row_ror:8 row_mask:0xf bank_mask:0xf bound_ctrl:1
	ds_read_b128 v[74:77], v95 offset:5120
	v_add_f32_dpp v112, v112, v112 row_ror:4 row_mask:0xf bank_mask:0xf bound_ctrl:1
	v_add_f32_dpp v114, v114, v114 row_ror:4 row_mask:0xf bank_mask:0xf bound_ctrl:1
	ds_read_b128 v[78:81], v95 offset:9216
	v_add_f32_dpp v112, v112, v112 row_ror:2 row_mask:0xf bank_mask:0xf bound_ctrl:1
	v_add_f32_dpp v114, v114, v114 row_ror:2 row_mask:0xf bank_mask:0xf bound_ctrl:1
	ds_read_b128 v[96:99], v95 offset:17408
	v_add_f32_dpp v112, v112, v112 row_ror:1 row_mask:0xf bank_mask:0xf bound_ctrl:1
	v_add_f32_dpp v114, v114, v114 row_ror:1 row_mask:0xf bank_mask:0xf bound_ctrl:1
	s_waitcnt lgkmcnt(8)
	v_pk_fma_f32 v[22:23], v[112:113], v[136:137], v[104:105] op_sel_hi:[0,1,1] neg_lo:[1,0,0] neg_hi:[1,0,0]
	v_pk_fma_f32 v[24:25], v[112:113], v[138:139], v[106:107] op_sel_hi:[0,1,1] neg_lo:[1,0,0] neg_hi:[1,0,0]
	ds_write_b32 v108, v114 offset:22656
	ds_read_b128 v[128:131], v95 offset:1280
	ds_read_b128 v[140:143], v95 offset:13568
	ds_read_b32 v148, v108 offset:20800
	s_waitcnt lgkmcnt(9)
	v_pk_mul_f32 v[102:103], v[22:23], v[70:71]
	s_waitcnt lgkmcnt(7)
	v_pk_mul_f32 v[104:105], v[82:83], v[100:101] op_sel_hi:[1,0]
	v_pk_fma_f32 v[102:103], v[24:25], v[72:73], v[102:103]
	v_pk_mul_f32 v[106:107], v[84:85], v[100:101] op_sel_hi:[1,0]
	v_pk_mul_f32 v[150:151], v[144:145], v[22:23]
	v_add_f32_e32 v112, v102, v103
	v_pk_fma_f32 v[150:151], v[146:147], v[24:25], v[150:151]
	s_waitcnt lgkmcnt(6)
	v_pk_fma_f32 v[104:105], v[22:23], v[74:75], v[104:105]
	v_add_f32_e32 v114, v150, v151
	v_pk_fma_f32 v[106:107], v[24:25], v[76:77], v[106:107]
	v_add_f32_dpp v112, v112, v112 row_ror:8 row_mask:0xf bank_mask:0xf bound_ctrl:1
	v_add_f32_dpp v114, v114, v114 row_ror:8 row_mask:0xf bank_mask:0xf bound_ctrl:1
	ds_read_b128 v[132:135], v95 offset:5376
	v_add_f32_dpp v112, v112, v112 row_ror:4 row_mask:0xf bank_mask:0xf bound_ctrl:1
	v_add_f32_dpp v114, v114, v114 row_ror:4 row_mask:0xf bank_mask:0xf bound_ctrl:1
	ds_read_b128 v[136:139], v95 offset:9472
	v_add_f32_dpp v112, v112, v112 row_ror:2 row_mask:0xf bank_mask:0xf bound_ctrl:1
	v_add_f32_dpp v114, v114, v114 row_ror:2 row_mask:0xf bank_mask:0xf bound_ctrl:1
	ds_read_b128 v[144:147], v95 offset:17664
	v_add_f32_dpp v112, v112, v112 row_ror:1 row_mask:0xf bank_mask:0xf bound_ctrl:1
	v_add_f32_dpp v114, v114, v114 row_ror:1 row_mask:0xf bank_mask:0xf bound_ctrl:1
	s_waitcnt lgkmcnt(8)
	v_pk_fma_f32 v[22:23], v[112:113], v[78:79], v[104:105] op_sel_hi:[0,1,1] neg_lo:[1,0,0] neg_hi:[1,0,0]
	v_pk_fma_f32 v[24:25], v[112:113], v[80:81], v[106:107] op_sel_hi:[0,1,1] neg_lo:[1,0,0] neg_hi:[1,0,0]
	ds_write_b32 v108, v114 offset:22720
	ds_read_b128 v[70:73], v95 offset:1536
	ds_read_b128 v[82:85], v95 offset:13824
	ds_read_b32 v100, v108 offset:20864
	s_waitcnt lgkmcnt(9)
	v_pk_mul_f32 v[102:103], v[22:23], v[128:129]
	s_waitcnt lgkmcnt(7)
	v_pk_mul_f32 v[104:105], v[140:141], v[148:149] op_sel_hi:[1,0]
	v_pk_fma_f32 v[102:103], v[24:25], v[130:131], v[102:103]
	v_pk_mul_f32 v[106:107], v[142:143], v[148:149] op_sel_hi:[1,0]
	v_pk_mul_f32 v[150:151], v[96:97], v[22:23]
	v_add_f32_e32 v112, v102, v103
	v_pk_fma_f32 v[150:151], v[98:99], v[24:25], v[150:151]
	s_waitcnt lgkmcnt(6)
	v_pk_fma_f32 v[104:105], v[22:23], v[132:133], v[104:105]
	v_add_f32_e32 v114, v150, v151
	v_pk_fma_f32 v[106:107], v[24:25], v[134:135], v[106:107]
	v_add_f32_dpp v112, v112, v112 row_ror:8 row_mask:0xf bank_mask:0xf bound_ctrl:1
	v_add_f32_dpp v114, v114, v114 row_ror:8 row_mask:0xf bank_mask:0xf bound_ctrl:1
	ds_read_b128 v[74:77], v95 offset:5632
	v_add_f32_dpp v112, v112, v112 row_ror:4 row_mask:0xf bank_mask:0xf bound_ctrl:1
	v_add_f32_dpp v114, v114, v114 row_ror:4 row_mask:0xf bank_mask:0xf bound_ctrl:1
	ds_read_b128 v[78:81], v95 offset:9728
	v_add_f32_dpp v112, v112, v112 row_ror:2 row_mask:0xf bank_mask:0xf bound_ctrl:1
	v_add_f32_dpp v114, v114, v114 row_ror:2 row_mask:0xf bank_mask:0xf bound_ctrl:1
	ds_read_b128 v[96:99], v95 offset:17920
	v_add_f32_dpp v112, v112, v112 row_ror:1 row_mask:0xf bank_mask:0xf bound_ctrl:1
	v_add_f32_dpp v114, v114, v114 row_ror:1 row_mask:0xf bank_mask:0xf bound_ctrl:1
	s_waitcnt lgkmcnt(8)
	v_pk_fma_f32 v[22:23], v[112:113], v[136:137], v[104:105] op_sel_hi:[0,1,1] neg_lo:[1,0,0] neg_hi:[1,0,0]
	v_pk_fma_f32 v[24:25], v[112:113], v[138:139], v[106:107] op_sel_hi:[0,1,1] neg_lo:[1,0,0] neg_hi:[1,0,0]
	ds_write_b32 v108, v114 offset:22784
	ds_read_b128 v[128:131], v95 offset:1792
	ds_read_b128 v[140:143], v95 offset:14080
	ds_read_b32 v148, v108 offset:20928
	s_waitcnt lgkmcnt(9)
	v_pk_mul_f32 v[102:103], v[22:23], v[70:71]
	s_waitcnt lgkmcnt(7)
	v_pk_mul_f32 v[104:105], v[82:83], v[100:101] op_sel_hi:[1,0]
	v_pk_fma_f32 v[102:103], v[24:25], v[72:73], v[102:103]
	v_pk_mul_f32 v[106:107], v[84:85], v[100:101] op_sel_hi:[1,0]
	v_pk_mul_f32 v[150:151], v[144:145], v[22:23]
	v_add_f32_e32 v112, v102, v103
	v_pk_fma_f32 v[150:151], v[146:147], v[24:25], v[150:151]
	s_waitcnt lgkmcnt(6)
	v_pk_fma_f32 v[104:105], v[22:23], v[74:75], v[104:105]
	v_add_f32_e32 v114, v150, v151
	v_pk_fma_f32 v[106:107], v[24:25], v[76:77], v[106:107]
	v_add_f32_dpp v112, v112, v112 row_ror:8 row_mask:0xf bank_mask:0xf bound_ctrl:1
	v_add_f32_dpp v114, v114, v114 row_ror:8 row_mask:0xf bank_mask:0xf bound_ctrl:1
	ds_read_b128 v[132:135], v95 offset:5888
	v_add_f32_dpp v112, v112, v112 row_ror:4 row_mask:0xf bank_mask:0xf bound_ctrl:1
	v_add_f32_dpp v114, v114, v114 row_ror:4 row_mask:0xf bank_mask:0xf bound_ctrl:1
	ds_read_b128 v[136:139], v95 offset:9984
	v_add_f32_dpp v112, v112, v112 row_ror:2 row_mask:0xf bank_mask:0xf bound_ctrl:1
	v_add_f32_dpp v114, v114, v114 row_ror:2 row_mask:0xf bank_mask:0xf bound_ctrl:1
	ds_read_b128 v[144:147], v95 offset:18176
	v_add_f32_dpp v112, v112, v112 row_ror:1 row_mask:0xf bank_mask:0xf bound_ctrl:1
	v_add_f32_dpp v114, v114, v114 row_ror:1 row_mask:0xf bank_mask:0xf bound_ctrl:1
	s_waitcnt lgkmcnt(8)
	v_pk_fma_f32 v[22:23], v[112:113], v[78:79], v[104:105] op_sel_hi:[0,1,1] neg_lo:[1,0,0] neg_hi:[1,0,0]
	v_pk_fma_f32 v[24:25], v[112:113], v[80:81], v[106:107] op_sel_hi:[0,1,1] neg_lo:[1,0,0] neg_hi:[1,0,0]
	ds_write_b32 v108, v114 offset:22848
	ds_read_b128 v[70:73], v95 offset:2048
	ds_read_b128 v[82:85], v95 offset:14336
	ds_read_b32 v100, v108 offset:20992
	s_waitcnt lgkmcnt(9)
	v_pk_mul_f32 v[102:103], v[22:23], v[128:129]
	s_waitcnt lgkmcnt(7)
	v_pk_mul_f32 v[104:105], v[140:141], v[148:149] op_sel_hi:[1,0]
	v_pk_fma_f32 v[102:103], v[24:25], v[130:131], v[102:103]
	v_pk_mul_f32 v[106:107], v[142:143], v[148:149] op_sel_hi:[1,0]
	v_pk_mul_f32 v[150:151], v[96:97], v[22:23]
	v_add_f32_e32 v112, v102, v103
	v_pk_fma_f32 v[150:151], v[98:99], v[24:25], v[150:151]
	s_waitcnt lgkmcnt(6)
	v_pk_fma_f32 v[104:105], v[22:23], v[132:133], v[104:105]
	v_add_f32_e32 v114, v150, v151
	v_pk_fma_f32 v[106:107], v[24:25], v[134:135], v[106:107]
	v_add_f32_dpp v112, v112, v112 row_ror:8 row_mask:0xf bank_mask:0xf bound_ctrl:1
	v_add_f32_dpp v114, v114, v114 row_ror:8 row_mask:0xf bank_mask:0xf bound_ctrl:1
	ds_read_b128 v[74:77], v95 offset:6144
	v_add_f32_dpp v112, v112, v112 row_ror:4 row_mask:0xf bank_mask:0xf bound_ctrl:1
	v_add_f32_dpp v114, v114, v114 row_ror:4 row_mask:0xf bank_mask:0xf bound_ctrl:1
	ds_read_b128 v[78:81], v95 offset:10240
	v_add_f32_dpp v112, v112, v112 row_ror:2 row_mask:0xf bank_mask:0xf bound_ctrl:1
	v_add_f32_dpp v114, v114, v114 row_ror:2 row_mask:0xf bank_mask:0xf bound_ctrl:1
	ds_read_b128 v[96:99], v95 offset:18432
	v_add_f32_dpp v112, v112, v112 row_ror:1 row_mask:0xf bank_mask:0xf bound_ctrl:1
	v_add_f32_dpp v114, v114, v114 row_ror:1 row_mask:0xf bank_mask:0xf bound_ctrl:1
	s_waitcnt lgkmcnt(8)
	v_pk_fma_f32 v[22:23], v[112:113], v[136:137], v[104:105] op_sel_hi:[0,1,1] neg_lo:[1,0,0] neg_hi:[1,0,0]
	v_pk_fma_f32 v[24:25], v[112:113], v[138:139], v[106:107] op_sel_hi:[0,1,1] neg_lo:[1,0,0] neg_hi:[1,0,0]
	ds_write_b32 v108, v114 offset:22912
	ds_read_b128 v[128:131], v95 offset:2304
	ds_read_b128 v[140:143], v95 offset:14592
	ds_read_b32 v148, v108 offset:21056
	s_waitcnt lgkmcnt(9)
	v_pk_mul_f32 v[102:103], v[22:23], v[70:71]
	s_waitcnt lgkmcnt(7)
	v_pk_mul_f32 v[104:105], v[82:83], v[100:101] op_sel_hi:[1,0]
	v_pk_fma_f32 v[102:103], v[24:25], v[72:73], v[102:103]
	v_pk_mul_f32 v[106:107], v[84:85], v[100:101] op_sel_hi:[1,0]
	v_pk_mul_f32 v[150:151], v[144:145], v[22:23]
	v_add_f32_e32 v112, v102, v103
	v_pk_fma_f32 v[150:151], v[146:147], v[24:25], v[150:151]
	s_waitcnt lgkmcnt(6)
	v_pk_fma_f32 v[104:105], v[22:23], v[74:75], v[104:105]
	v_add_f32_e32 v114, v150, v151
	v_pk_fma_f32 v[106:107], v[24:25], v[76:77], v[106:107]
	v_add_f32_dpp v112, v112, v112 row_ror:8 row_mask:0xf bank_mask:0xf bound_ctrl:1
	v_add_f32_dpp v114, v114, v114 row_ror:8 row_mask:0xf bank_mask:0xf bound_ctrl:1
	ds_read_b128 v[132:135], v95 offset:6400
	v_add_f32_dpp v112, v112, v112 row_ror:4 row_mask:0xf bank_mask:0xf bound_ctrl:1
	v_add_f32_dpp v114, v114, v114 row_ror:4 row_mask:0xf bank_mask:0xf bound_ctrl:1
	ds_read_b128 v[136:139], v95 offset:10496
	v_add_f32_dpp v112, v112, v112 row_ror:2 row_mask:0xf bank_mask:0xf bound_ctrl:1
	v_add_f32_dpp v114, v114, v114 row_ror:2 row_mask:0xf bank_mask:0xf bound_ctrl:1
	ds_read_b128 v[144:147], v95 offset:18688
	v_add_f32_dpp v112, v112, v112 row_ror:1 row_mask:0xf bank_mask:0xf bound_ctrl:1
	v_add_f32_dpp v114, v114, v114 row_ror:1 row_mask:0xf bank_mask:0xf bound_ctrl:1
	s_waitcnt lgkmcnt(8)
	v_pk_fma_f32 v[22:23], v[112:113], v[78:79], v[104:105] op_sel_hi:[0,1,1] neg_lo:[1,0,0] neg_hi:[1,0,0]
	v_pk_fma_f32 v[24:25], v[112:113], v[80:81], v[106:107] op_sel_hi:[0,1,1] neg_lo:[1,0,0] neg_hi:[1,0,0]
	ds_write_b32 v108, v114 offset:22976
	ds_read_b128 v[70:73], v95 offset:2560
	ds_read_b128 v[82:85], v95 offset:14848
	ds_read_b32 v100, v108 offset:21120
	s_waitcnt lgkmcnt(9)
	v_pk_mul_f32 v[102:103], v[22:23], v[128:129]
	s_waitcnt lgkmcnt(7)
	v_pk_mul_f32 v[104:105], v[140:141], v[148:149] op_sel_hi:[1,0]
	v_pk_fma_f32 v[102:103], v[24:25], v[130:131], v[102:103]
	v_pk_mul_f32 v[106:107], v[142:143], v[148:149] op_sel_hi:[1,0]
	v_pk_mul_f32 v[150:151], v[96:97], v[22:23]
	v_add_f32_e32 v112, v102, v103
	v_pk_fma_f32 v[150:151], v[98:99], v[24:25], v[150:151]
	s_waitcnt lgkmcnt(6)
	v_pk_fma_f32 v[104:105], v[22:23], v[132:133], v[104:105]
	v_add_f32_e32 v114, v150, v151
	v_pk_fma_f32 v[106:107], v[24:25], v[134:135], v[106:107]
	v_add_f32_dpp v112, v112, v112 row_ror:8 row_mask:0xf bank_mask:0xf bound_ctrl:1
	v_add_f32_dpp v114, v114, v114 row_ror:8 row_mask:0xf bank_mask:0xf bound_ctrl:1
	ds_read_b128 v[74:77], v95 offset:6656
	v_add_f32_dpp v112, v112, v112 row_ror:4 row_mask:0xf bank_mask:0xf bound_ctrl:1
	v_add_f32_dpp v114, v114, v114 row_ror:4 row_mask:0xf bank_mask:0xf bound_ctrl:1
	ds_read_b128 v[78:81], v95 offset:10752
	v_add_f32_dpp v112, v112, v112 row_ror:2 row_mask:0xf bank_mask:0xf bound_ctrl:1
	v_add_f32_dpp v114, v114, v114 row_ror:2 row_mask:0xf bank_mask:0xf bound_ctrl:1
	ds_read_b128 v[96:99], v95 offset:18944
	v_add_f32_dpp v112, v112, v112 row_ror:1 row_mask:0xf bank_mask:0xf bound_ctrl:1
	v_add_f32_dpp v114, v114, v114 row_ror:1 row_mask:0xf bank_mask:0xf bound_ctrl:1
	s_waitcnt lgkmcnt(8)
	v_pk_fma_f32 v[22:23], v[112:113], v[136:137], v[104:105] op_sel_hi:[0,1,1] neg_lo:[1,0,0] neg_hi:[1,0,0]
	v_pk_fma_f32 v[24:25], v[112:113], v[138:139], v[106:107] op_sel_hi:[0,1,1] neg_lo:[1,0,0] neg_hi:[1,0,0]
	ds_write_b32 v108, v114 offset:23040
	ds_read_b128 v[128:131], v95 offset:2816
	ds_read_b128 v[140:143], v95 offset:15104
	ds_read_b32 v148, v108 offset:21184
	s_waitcnt lgkmcnt(9)
	v_pk_mul_f32 v[102:103], v[22:23], v[70:71]
	s_waitcnt lgkmcnt(7)
	v_pk_mul_f32 v[104:105], v[82:83], v[100:101] op_sel_hi:[1,0]
	v_pk_fma_f32 v[102:103], v[24:25], v[72:73], v[102:103]
	v_pk_mul_f32 v[106:107], v[84:85], v[100:101] op_sel_hi:[1,0]
	v_pk_mul_f32 v[150:151], v[144:145], v[22:23]
	v_add_f32_e32 v112, v102, v103
	v_pk_fma_f32 v[150:151], v[146:147], v[24:25], v[150:151]
	s_waitcnt lgkmcnt(6)
	v_pk_fma_f32 v[104:105], v[22:23], v[74:75], v[104:105]
	v_add_f32_e32 v114, v150, v151
	v_pk_fma_f32 v[106:107], v[24:25], v[76:77], v[106:107]
	v_add_f32_dpp v112, v112, v112 row_ror:8 row_mask:0xf bank_mask:0xf bound_ctrl:1
	v_add_f32_dpp v114, v114, v114 row_ror:8 row_mask:0xf bank_mask:0xf bound_ctrl:1
	ds_read_b128 v[132:135], v95 offset:6912
	v_add_f32_dpp v112, v112, v112 row_ror:4 row_mask:0xf bank_mask:0xf bound_ctrl:1
	v_add_f32_dpp v114, v114, v114 row_ror:4 row_mask:0xf bank_mask:0xf bound_ctrl:1
	ds_read_b128 v[136:139], v95 offset:11008
	v_add_f32_dpp v112, v112, v112 row_ror:2 row_mask:0xf bank_mask:0xf bound_ctrl:1
	v_add_f32_dpp v114, v114, v114 row_ror:2 row_mask:0xf bank_mask:0xf bound_ctrl:1
	ds_read_b128 v[144:147], v95 offset:19200
	v_add_f32_dpp v112, v112, v112 row_ror:1 row_mask:0xf bank_mask:0xf bound_ctrl:1
	v_add_f32_dpp v114, v114, v114 row_ror:1 row_mask:0xf bank_mask:0xf bound_ctrl:1
	s_waitcnt lgkmcnt(8)
	v_pk_fma_f32 v[22:23], v[112:113], v[78:79], v[104:105] op_sel_hi:[0,1,1] neg_lo:[1,0,0] neg_hi:[1,0,0]
	v_pk_fma_f32 v[24:25], v[112:113], v[80:81], v[106:107] op_sel_hi:[0,1,1] neg_lo:[1,0,0] neg_hi:[1,0,0]
	ds_write_b32 v108, v114 offset:23104
	ds_read_b128 v[70:73], v95 offset:3072
	ds_read_b128 v[82:85], v95 offset:15360
	ds_read_b32 v100, v108 offset:21248
	s_waitcnt lgkmcnt(9)
	v_pk_mul_f32 v[102:103], v[22:23], v[128:129]
	s_waitcnt lgkmcnt(7)
	v_pk_mul_f32 v[104:105], v[140:141], v[148:149] op_sel_hi:[1,0]
	v_pk_fma_f32 v[102:103], v[24:25], v[130:131], v[102:103]
	v_pk_mul_f32 v[106:107], v[142:143], v[148:149] op_sel_hi:[1,0]
	v_pk_mul_f32 v[150:151], v[96:97], v[22:23]
	v_add_f32_e32 v112, v102, v103
	v_pk_fma_f32 v[150:151], v[98:99], v[24:25], v[150:151]
	s_waitcnt lgkmcnt(6)
	v_pk_fma_f32 v[104:105], v[22:23], v[132:133], v[104:105]
	v_add_f32_e32 v114, v150, v151
	v_pk_fma_f32 v[106:107], v[24:25], v[134:135], v[106:107]
	v_add_f32_dpp v112, v112, v112 row_ror:8 row_mask:0xf bank_mask:0xf bound_ctrl:1
	v_add_f32_dpp v114, v114, v114 row_ror:8 row_mask:0xf bank_mask:0xf bound_ctrl:1
	ds_read_b128 v[74:77], v95 offset:7168
	v_add_f32_dpp v112, v112, v112 row_ror:4 row_mask:0xf bank_mask:0xf bound_ctrl:1
	v_add_f32_dpp v114, v114, v114 row_ror:4 row_mask:0xf bank_mask:0xf bound_ctrl:1
	ds_read_b128 v[78:81], v95 offset:11264
	v_add_f32_dpp v112, v112, v112 row_ror:2 row_mask:0xf bank_mask:0xf bound_ctrl:1
	v_add_f32_dpp v114, v114, v114 row_ror:2 row_mask:0xf bank_mask:0xf bound_ctrl:1
	ds_read_b128 v[96:99], v95 offset:19456
	v_add_f32_dpp v112, v112, v112 row_ror:1 row_mask:0xf bank_mask:0xf bound_ctrl:1
	v_add_f32_dpp v114, v114, v114 row_ror:1 row_mask:0xf bank_mask:0xf bound_ctrl:1
	s_waitcnt lgkmcnt(8)
	v_pk_fma_f32 v[22:23], v[112:113], v[136:137], v[104:105] op_sel_hi:[0,1,1] neg_lo:[1,0,0] neg_hi:[1,0,0]
	v_pk_fma_f32 v[24:25], v[112:113], v[138:139], v[106:107] op_sel_hi:[0,1,1] neg_lo:[1,0,0] neg_hi:[1,0,0]
	ds_write_b32 v108, v114 offset:23168
	ds_read_b128 v[128:131], v95 offset:3328
	ds_read_b128 v[140:143], v95 offset:15616
	ds_read_b32 v148, v108 offset:21312
	s_waitcnt lgkmcnt(9)
	v_pk_mul_f32 v[102:103], v[22:23], v[70:71]
	s_waitcnt lgkmcnt(7)
	v_pk_mul_f32 v[104:105], v[82:83], v[100:101] op_sel_hi:[1,0]
	v_pk_fma_f32 v[102:103], v[24:25], v[72:73], v[102:103]
	v_pk_mul_f32 v[106:107], v[84:85], v[100:101] op_sel_hi:[1,0]
	v_pk_mul_f32 v[150:151], v[144:145], v[22:23]
	v_add_f32_e32 v112, v102, v103
	v_pk_fma_f32 v[150:151], v[146:147], v[24:25], v[150:151]
	s_waitcnt lgkmcnt(6)
	v_pk_fma_f32 v[104:105], v[22:23], v[74:75], v[104:105]
	v_add_f32_e32 v114, v150, v151
	v_pk_fma_f32 v[106:107], v[24:25], v[76:77], v[106:107]
	v_add_f32_dpp v112, v112, v112 row_ror:8 row_mask:0xf bank_mask:0xf bound_ctrl:1
	v_add_f32_dpp v114, v114, v114 row_ror:8 row_mask:0xf bank_mask:0xf bound_ctrl:1
	ds_read_b128 v[132:135], v95 offset:7424
	v_add_f32_dpp v112, v112, v112 row_ror:4 row_mask:0xf bank_mask:0xf bound_ctrl:1
	v_add_f32_dpp v114, v114, v114 row_ror:4 row_mask:0xf bank_mask:0xf bound_ctrl:1
	ds_read_b128 v[136:139], v95 offset:11520
	v_add_f32_dpp v112, v112, v112 row_ror:2 row_mask:0xf bank_mask:0xf bound_ctrl:1
	v_add_f32_dpp v114, v114, v114 row_ror:2 row_mask:0xf bank_mask:0xf bound_ctrl:1
	ds_read_b128 v[144:147], v95 offset:19712
	v_add_f32_dpp v112, v112, v112 row_ror:1 row_mask:0xf bank_mask:0xf bound_ctrl:1
	v_add_f32_dpp v114, v114, v114 row_ror:1 row_mask:0xf bank_mask:0xf bound_ctrl:1
	s_waitcnt lgkmcnt(8)
	v_pk_fma_f32 v[22:23], v[112:113], v[78:79], v[104:105] op_sel_hi:[0,1,1] neg_lo:[1,0,0] neg_hi:[1,0,0]
	v_pk_fma_f32 v[24:25], v[112:113], v[80:81], v[106:107] op_sel_hi:[0,1,1] neg_lo:[1,0,0] neg_hi:[1,0,0]
	ds_write_b32 v108, v114 offset:23232
	ds_read_b128 v[70:73], v95 offset:3584
	ds_read_b128 v[82:85], v95 offset:15872
	ds_read_b32 v100, v108 offset:21376
	s_waitcnt lgkmcnt(9)
	v_pk_mul_f32 v[102:103], v[22:23], v[128:129]
	s_waitcnt lgkmcnt(7)
	v_pk_mul_f32 v[104:105], v[140:141], v[148:149] op_sel_hi:[1,0]
	v_pk_fma_f32 v[102:103], v[24:25], v[130:131], v[102:103]
	v_pk_mul_f32 v[106:107], v[142:143], v[148:149] op_sel_hi:[1,0]
	v_pk_mul_f32 v[150:151], v[96:97], v[22:23]
	v_add_f32_e32 v112, v102, v103
	v_pk_fma_f32 v[150:151], v[98:99], v[24:25], v[150:151]
	s_waitcnt lgkmcnt(6)
	v_pk_fma_f32 v[104:105], v[22:23], v[132:133], v[104:105]
	v_add_f32_e32 v114, v150, v151
	v_pk_fma_f32 v[106:107], v[24:25], v[134:135], v[106:107]
	v_add_f32_dpp v112, v112, v112 row_ror:8 row_mask:0xf bank_mask:0xf bound_ctrl:1
	v_add_f32_dpp v114, v114, v114 row_ror:8 row_mask:0xf bank_mask:0xf bound_ctrl:1
	ds_read_b128 v[74:77], v95 offset:7680
	v_add_f32_dpp v112, v112, v112 row_ror:4 row_mask:0xf bank_mask:0xf bound_ctrl:1
	v_add_f32_dpp v114, v114, v114 row_ror:4 row_mask:0xf bank_mask:0xf bound_ctrl:1
	ds_read_b128 v[78:81], v95 offset:11776
	v_add_f32_dpp v112, v112, v112 row_ror:2 row_mask:0xf bank_mask:0xf bound_ctrl:1
	v_add_f32_dpp v114, v114, v114 row_ror:2 row_mask:0xf bank_mask:0xf bound_ctrl:1
	ds_read_b128 v[96:99], v95 offset:19968
	v_add_f32_dpp v112, v112, v112 row_ror:1 row_mask:0xf bank_mask:0xf bound_ctrl:1
	v_add_f32_dpp v114, v114, v114 row_ror:1 row_mask:0xf bank_mask:0xf bound_ctrl:1
	s_waitcnt lgkmcnt(8)
	v_pk_fma_f32 v[22:23], v[112:113], v[136:137], v[104:105] op_sel_hi:[0,1,1] neg_lo:[1,0,0] neg_hi:[1,0,0]
	v_pk_fma_f32 v[24:25], v[112:113], v[138:139], v[106:107] op_sel_hi:[0,1,1] neg_lo:[1,0,0] neg_hi:[1,0,0]
	ds_write_b32 v108, v114 offset:23296
	ds_read_b128 v[128:131], v95 offset:3840
	ds_read_b128 v[140:143], v95 offset:16128
	ds_read_b32 v148, v108 offset:21440
	s_waitcnt lgkmcnt(9)
	v_pk_mul_f32 v[102:103], v[22:23], v[70:71]
	s_waitcnt lgkmcnt(7)
	v_pk_mul_f32 v[104:105], v[82:83], v[100:101] op_sel_hi:[1,0]
	v_pk_fma_f32 v[102:103], v[24:25], v[72:73], v[102:103]
	v_pk_mul_f32 v[106:107], v[84:85], v[100:101] op_sel_hi:[1,0]
	v_pk_mul_f32 v[150:151], v[144:145], v[22:23]
	v_add_f32_e32 v112, v102, v103
	v_pk_fma_f32 v[150:151], v[146:147], v[24:25], v[150:151]
	s_waitcnt lgkmcnt(6)
	v_pk_fma_f32 v[104:105], v[22:23], v[74:75], v[104:105]
	v_add_f32_e32 v114, v150, v151
	v_pk_fma_f32 v[106:107], v[24:25], v[76:77], v[106:107]
	v_add_f32_dpp v112, v112, v112 row_ror:8 row_mask:0xf bank_mask:0xf bound_ctrl:1
	v_add_f32_dpp v114, v114, v114 row_ror:8 row_mask:0xf bank_mask:0xf bound_ctrl:1
	ds_read_b128 v[132:135], v95 offset:7936
	v_add_f32_dpp v112, v112, v112 row_ror:4 row_mask:0xf bank_mask:0xf bound_ctrl:1
	v_add_f32_dpp v114, v114, v114 row_ror:4 row_mask:0xf bank_mask:0xf bound_ctrl:1
	ds_read_b128 v[136:139], v95 offset:12032
	v_add_f32_dpp v112, v112, v112 row_ror:2 row_mask:0xf bank_mask:0xf bound_ctrl:1
	v_add_f32_dpp v114, v114, v114 row_ror:2 row_mask:0xf bank_mask:0xf bound_ctrl:1
	ds_read_b128 v[144:147], v95 offset:20224
	v_add_f32_dpp v112, v112, v112 row_ror:1 row_mask:0xf bank_mask:0xf bound_ctrl:1
	v_add_f32_dpp v114, v114, v114 row_ror:1 row_mask:0xf bank_mask:0xf bound_ctrl:1
	s_waitcnt lgkmcnt(8)
	v_pk_fma_f32 v[22:23], v[112:113], v[78:79], v[104:105] op_sel_hi:[0,1,1] neg_lo:[1,0,0] neg_hi:[1,0,0]
	v_pk_fma_f32 v[24:25], v[112:113], v[80:81], v[106:107] op_sel_hi:[0,1,1] neg_lo:[1,0,0] neg_hi:[1,0,0]
	ds_write_b32 v108, v114 offset:23360
	s_waitcnt lgkmcnt(6)
	v_pk_mul_f32 v[102:103], v[22:23], v[128:129]
	s_waitcnt lgkmcnt(4)
	v_pk_mul_f32 v[104:105], v[140:141], v[148:149] op_sel_hi:[1,0]
	v_pk_fma_f32 v[102:103], v[24:25], v[130:131], v[102:103]
	v_pk_mul_f32 v[106:107], v[142:143], v[148:149] op_sel_hi:[1,0]
	v_pk_mul_f32 v[150:151], v[96:97], v[22:23]
	v_add_f32_e32 v112, v102, v103
	v_pk_fma_f32 v[150:151], v[98:99], v[24:25], v[150:151]
	s_waitcnt lgkmcnt(3)
	v_pk_fma_f32 v[104:105], v[22:23], v[132:133], v[104:105]
	v_add_f32_e32 v114, v150, v151
	v_pk_fma_f32 v[106:107], v[24:25], v[134:135], v[106:107]
	v_add_f32_dpp v112, v112, v112 row_ror:8 row_mask:0xf bank_mask:0xf bound_ctrl:1
	v_add_f32_dpp v114, v114, v114 row_ror:8 row_mask:0xf bank_mask:0xf bound_ctrl:1
	s_nop 0
	v_add_f32_dpp v112, v112, v112 row_ror:4 row_mask:0xf bank_mask:0xf bound_ctrl:1
	s_nop 0
	v_add_f32_dpp v114, v114, v114 row_ror:4 row_mask:0xf bank_mask:0xf bound_ctrl:1
	s_nop 0
	v_add_f32_dpp v112, v112, v112 row_ror:2 row_mask:0xf bank_mask:0xf bound_ctrl:1
	s_nop 0
	v_add_f32_dpp v114, v114, v114 row_ror:2 row_mask:0xf bank_mask:0xf bound_ctrl:1
	s_nop 0
	v_add_f32_dpp v112, v112, v112 row_ror:1 row_mask:0xf bank_mask:0xf bound_ctrl:1
	s_nop 0
	v_add_f32_dpp v114, v114, v114 row_ror:1 row_mask:0xf bank_mask:0xf bound_ctrl:1
	s_waitcnt lgkmcnt(2)
	v_pk_fma_f32 v[22:23], v[112:113], v[136:137], v[104:105] op_sel_hi:[0,1,1] neg_lo:[1,0,0] neg_hi:[1,0,0]
	v_pk_fma_f32 v[24:25], v[112:113], v[138:139], v[106:107] op_sel_hi:[0,1,1] neg_lo:[1,0,0] neg_hi:[1,0,0]
	ds_write_b32 v108, v114 offset:23424
	s_waitcnt lgkmcnt(2)
	v_pk_mul_f32 v[150:151], v[144:145], v[22:23]
	v_pk_fma_f32 v[150:151], v[146:147], v[24:25], v[150:151]
	v_add_f32_e32 v114, v150, v151
	s_nop 1
	v_add_f32_dpp v114, v114, v114 row_ror:8 row_mask:0xf bank_mask:0xf bound_ctrl:1
	s_nop 1
	v_add_f32_dpp v114, v114, v114 row_ror:4 row_mask:0xf bank_mask:0xf bound_ctrl:1
	s_nop 1
	v_add_f32_dpp v114, v114, v114 row_ror:2 row_mask:0xf bank_mask:0xf bound_ctrl:1
	s_nop 1
	v_add_f32_dpp v114, v114, v114 row_ror:1 row_mask:0xf bank_mask:0xf bound_ctrl:1
	ds_write_b32 v108, v114 offset:23488
	s_add_u32 s28, s28, 16
	s_cmp_lt_u32 s28, s25
	s_cbranch_scc1 .Lrw0_loop
	s_waitcnt lgkmcnt(0)
	s_barrier
	ds_read_b32 v89, v115 offset:22528
	s_sub_u32 s98, s28, 16
	v_add_u32_e32 v87, s98, v127
	v_mad_i64_i32 v[104:105], vcc, v87, v20, v[18:19]
	s_waitcnt lgkmcnt(0)
	v_cvt_pk_bf16_f32 v89, v89, v89
	global_store_short v[104:105], v89, off
	v_lshl_add_u32 v87, s17, 4, v127
	v_lshl_add_u32 v89, v87, 8, v95
	s_cmp_eq_u32 s18, 3
	s_cbranch_scc0 .Lrw0_f_not3
	s_load_dwordx2 s[36:37], s[14:15], 0x120
	s_waitcnt lgkmcnt(0)
	s_lshl_b32 s98, s42, 14
	s_add_u32 s36, s36, s98
	s_addc_u32 s37, s37, 0
	s_add_u32 s36, s36, 0x5e00000
	s_addc_u32 s37, s37, 0
	global_store_dwordx4 v89, v[22:25], s[36:37]
	s_branch .Lrw0_f_done
